# attention: removed 96 redundant fmaxf-canonicalising v_max (x,x) on the softmax max->compare->branch chain (48 sites), on top of v39
# baseline (speedup 1.0000x reference)
; __device__ __forceinline__ float max3f(float a, float b, float c) { return fmaxf(fmaxf(a, b), c); }
; __device__ __forceinline__ float max2f(float a, float b) { return fmaxf(a, b); }
; __device__ __forceinline__ void softmax_head(f32x16& s, int kb, int lq, int radius, bool full, int hi, HState& S) {
;     ...
;     float t0 = max3f(s[0], s[1], s[2]), t1 = max3f(s[3], s[4], s[5]);
;     t0 = max3f(t0, s[6], s[7]); t1 = max3f(t1, s[8], s[9]); t0 = max3f(t0, s[10], s[11]); t1 = max3f(t1, s[12], s[13]);
;     float tmax = max3f(t0, s[14], s[15]); tmax = max2f(tmax, t1);
;     { auto rr = __builtin_amdgcn_permlane32_swap(__float_as_uint(tmax), __float_as_uint(tmax), false, false); tmax = max2f(__uint_as_float(rr[0]), __uint_as_float(rr[1])); }
;     if (__builtin_amdgcn_ballot_w64(tmax > S.m + 8.0f) != 0ull) {
;         const float mn = max2f(S.m, tmax), alpha = __builtin_amdgcn_exp2f(S.m - mn); S.m = mn; S.l *= alpha;
; #pragma unroll
;         for (int dh = 0; dh < 2; ++dh)
; #pragma unroll
;             for (int r = 0; r < 16; ++r) S.o[dh][r] *= alpha;
;     }
.LBB0_424:
	s_nop 6
	v_max_f32_e32 v100, v80, v81
	v_max3_f32 v101, v83, v84, v85
	v_max3_f32 v100, v100, v82, v86
	v_max3_f32 v101, v101, v88, v89
	v_max3_f32 v100, v100, v87, v90
	v_max3_f32 v101, v101, v92, v93
	v_max3_f32 v100, v100, v91, v94
	v_max3_f32 v100, v100, v95, v101
	v_mov_b32_e32 v101, v100
	s_nop 1
	v_permlane32_swap_b32_e32 v100, v101
	v_max_f32_e32 v100, v100, v101
	v_add_f32_e32 v101, 0x41000000, v184
	v_cmp_gt_f32_e32 vcc, v100, v101
	s_cbranch_vccz .LBB0_426
	v_max_f32_e32 v100, v100, v100
	v_max_f32_e32 v101, v184, v184
	v_max_f32_e32 v101, v101, v100
	v_sub_f32_e32 v100, v184, v101
	v_exp_f32_e32 v100, v100
	v_mov_b32_e32 v184, v101
	v_mul_f32_e32 v197, v197, v100
	v_pk_mul_f32 v[78:79], v[78:79], v[100:101] op_sel_hi:[1,0]
	v_pk_mul_f32 v[76:77], v[76:77], v[100:101] op_sel_hi:[1,0]
	v_pk_mul_f32 v[74:75], v[74:75], v[100:101] op_sel_hi:[1,0]
	v_pk_mul_f32 v[72:73], v[72:73], v[100:101] op_sel_hi:[1,0]
	v_pk_mul_f32 v[70:71], v[70:71], v[100:101] op_sel_hi:[1,0]
	v_pk_mul_f32 v[68:69], v[68:69], v[100:101] op_sel_hi:[1,0]
	v_pk_mul_f32 v[66:67], v[66:67], v[100:101] op_sel_hi:[1,0]
	v_pk_mul_f32 v[64:65], v[64:65], v[100:101] op_sel_hi:[1,0]
	v_pk_mul_f32 v[62:63], v[62:63], v[100:101] op_sel_hi:[1,0]
	v_pk_mul_f32 v[60:61], v[60:61], v[100:101] op_sel_hi:[1,0]
	v_pk_mul_f32 v[58:59], v[58:59], v[100:101] op_sel_hi:[1,0]
	v_pk_mul_f32 v[56:57], v[56:57], v[100:101] op_sel_hi:[1,0]
	v_pk_mul_f32 v[54:55], v[54:55], v[100:101] op_sel_hi:[1,0]
	v_pk_mul_f32 v[52:53], v[52:53], v[100:101] op_sel_hi:[1,0]
	v_pk_mul_f32 v[50:51], v[50:51], v[100:101] op_sel_hi:[1,0]
	v_pk_mul_f32 v[48:49], v[48:49], v[100:101] op_sel_hi:[1,0]

; __device__ __forceinline__ float max3f(float a, float b, float c) { return fmaxf(fmaxf(a, b), c); }
; __device__ __forceinline__ float max2f(float a, float b) { return fmaxf(a, b); }
; __device__ __forceinline__ void softmax_head(f32x16& s, int kb, int lq, int radius, bool full, int hi, HState& S) {
;     ...
;     float t0 = max3f(s[0], s[1], s[2]), t1 = max3f(s[3], s[4], s[5]);
;     t0 = max3f(t0, s[6], s[7]); t1 = max3f(t1, s[8], s[9]); t0 = max3f(t0, s[10], s[11]); t1 = max3f(t1, s[12], s[13]);
;     float tmax = max3f(t0, s[14], s[15]); tmax = max2f(tmax, t1);
;     { auto rr = __builtin_amdgcn_permlane32_swap(__float_as_uint(tmax), __float_as_uint(tmax), false, false); tmax = max2f(__uint_as_float(rr[0]), __uint_as_float(rr[1])); }
;     if (__builtin_amdgcn_ballot_w64(tmax > S.m + 8.0f) != 0ull) {
;         const float mn = max2f(S.m, tmax), alpha = __builtin_amdgcn_exp2f(S.m - mn); S.m = mn; S.l *= alpha;
; #pragma unroll
;         for (int dh = 0; dh < 2; ++dh)
; #pragma unroll
;             for (int r = 0; r < 16; ++r) S.o[dh][r] *= alpha;
;     }
.LBB0_428:
	s_nop 9
	v_max_f32_e32 v15, v96, v97
	v_max3_f32 v148, v99, v100, v101
	v_max3_f32 v15, v15, v98, v102
	v_max3_f32 v148, v148, v104, v105
	v_max3_f32 v15, v15, v103, v106
	v_max3_f32 v148, v148, v108, v109
	v_max3_f32 v15, v15, v107, v110
	v_max3_f32 v15, v15, v111, v148
	v_mov_b32_e32 v148, v15
	s_nop 1
	v_permlane32_swap_b32_e32 v15, v148
	v_max_f32_e32 v15, v15, v148
	v_add_f32_e32 v148, 0x41000000, v183
	v_cmp_gt_f32_e32 vcc, v15, v148
	s_cbranch_vccz .LBB0_430
	v_max_f32_e32 v15, v15, v15
	v_max_f32_e32 v148, v183, v183
	v_max_f32_e32 v15, v148, v15
	v_sub_f32_e32 v148, v183, v15
	v_exp_f32_e32 v148, v148
	v_mov_b32_e32 v183, v15
	v_mul_f32_e32 v185, v185, v148
	v_pk_mul_f32 v[46:47], v[46:47], v[148:149] op_sel_hi:[1,0]
	v_pk_mul_f32 v[44:45], v[44:45], v[148:149] op_sel_hi:[1,0]
	v_pk_mul_f32 v[42:43], v[42:43], v[148:149] op_sel_hi:[1,0]
	v_pk_mul_f32 v[40:41], v[40:41], v[148:149] op_sel_hi:[1,0]
	v_pk_mul_f32 v[38:39], v[38:39], v[148:149] op_sel_hi:[1,0]
	v_pk_mul_f32 v[36:37], v[36:37], v[148:149] op_sel_hi:[1,0]
	v_pk_mul_f32 v[34:35], v[34:35], v[148:149] op_sel_hi:[1,0]
	v_pk_mul_f32 v[32:33], v[32:33], v[148:149] op_sel_hi:[1,0]
	v_pk_mul_f32 v[30:31], v[30:31], v[148:149] op_sel_hi:[1,0]
	v_pk_mul_f32 v[28:29], v[28:29], v[148:149] op_sel_hi:[1,0]
	v_pk_mul_f32 v[26:27], v[26:27], v[148:149] op_sel_hi:[1,0]
	v_pk_mul_f32 v[24:25], v[24:25], v[148:149] op_sel_hi:[1,0]
	v_pk_mul_f32 v[22:23], v[22:23], v[148:149] op_sel_hi:[1,0]
	v_pk_mul_f32 v[20:21], v[20:21], v[148:149] op_sel_hi:[1,0]
	v_pk_mul_f32 v[18:19], v[18:19], v[148:149] op_sel_hi:[1,0]
	v_pk_mul_f32 v[16:17], v[16:17], v[148:149] op_sel_hi:[1,0]

; __device__ __forceinline__ float max3f(float a, float b, float c) { return fmaxf(fmaxf(a, b), c); }
; __device__ __forceinline__ float max2f(float a, float b) { return fmaxf(a, b); }
; __device__ __forceinline__ void softmax_head(f32x16& s, int kb, int lq, int radius, bool full, int hi, HState& S) {
;     ...
;     float t0 = max3f(s[0], s[1], s[2]), t1 = max3f(s[3], s[4], s[5]);
;     t0 = max3f(t0, s[6], s[7]); t1 = max3f(t1, s[8], s[9]); t0 = max3f(t0, s[10], s[11]); t1 = max3f(t1, s[12], s[13]);
;     float tmax = max3f(t0, s[14], s[15]); tmax = max2f(tmax, t1);
;     { auto rr = __builtin_amdgcn_permlane32_swap(__float_as_uint(tmax), __float_as_uint(tmax), false, false); tmax = max2f(__uint_as_float(rr[0]), __uint_as_float(rr[1])); }
;     if (__builtin_amdgcn_ballot_w64(tmax > S.m + 8.0f) != 0ull) {
;         const float mn = max2f(S.m, tmax), alpha = __builtin_amdgcn_exp2f(S.m - mn); S.m = mn; S.l *= alpha;
; #pragma unroll
;         for (int dh = 0; dh < 2; ++dh)
; #pragma unroll
;             for (int r = 0; r < 16; ++r) S.o[dh][r] *= alpha;
;     }
; __device__ __forceinline__ void softmax_tail(f32x16& s, HState& S, u32x4 (&pw)[2]) {
;     ...
;     for (int r = 2; r < 16; r += 2) { p0 += s[r]; p1 += s[r + 1]; }
;     S.l += p0 + p1;
.LBB0_432:
	v_add_f32_e32 v14, v233, v235
	v_add_f32_e32 v100, v234, v236
	v_add_f32_e32 v14, v237, v14
	v_add_f32_e32 v100, v238, v100
	v_add_f32_e32 v14, v239, v14
	v_add_f32_e32 v100, v240, v100
	v_add_f32_e32 v14, v241, v14
	v_add_f32_e32 v100, v242, v100
	v_add_f32_e32 v14, v243, v14
	v_add_f32_e32 v100, v244, v100
	v_add_f32_e32 v14, v245, v14
	v_add_f32_e32 v100, v246, v100
	v_add_f32_e32 v14, v247, v14
	v_add_f32_e32 v100, v248, v100
	v_add_f32_e32 v14, v14, v100
	v_max_f32_e32 v100, v80, v81
	v_max3_f32 v101, v83, v84, v85
	v_max3_f32 v100, v100, v82, v86
	v_max3_f32 v101, v101, v88, v89
	v_max3_f32 v100, v100, v87, v90
	v_max3_f32 v101, v101, v92, v93
	v_max3_f32 v100, v100, v91, v94
	v_max3_f32 v100, v100, v95, v101
	v_mov_b32_e32 v101, v100
	s_nop 1
	v_permlane32_swap_b32_e32 v100, v101
	v_max_f32_e32 v100, v100, v101
	v_add_f32_e32 v101, 0x41000000, v184
	v_add_f32_e32 v14, v197, v14
	v_cmp_gt_f32_e32 vcc, v100, v101
	s_cbranch_vccz .LBB0_434
	v_max_f32_e32 v100, v100, v100
	v_max_f32_e32 v101, v184, v184
	v_max_f32_e32 v101, v101, v100
	v_sub_f32_e32 v100, v184, v101
	v_exp_f32_e32 v100, v100
	v_mov_b32_e32 v184, v101
	v_mul_f32_e32 v14, v14, v100
	v_pk_mul_f32 v[78:79], v[78:79], v[100:101] op_sel_hi:[1,0]
	v_pk_mul_f32 v[76:77], v[76:77], v[100:101] op_sel_hi:[1,0]
	v_pk_mul_f32 v[74:75], v[74:75], v[100:101] op_sel_hi:[1,0]
	v_pk_mul_f32 v[72:73], v[72:73], v[100:101] op_sel_hi:[1,0]
	v_pk_mul_f32 v[70:71], v[70:71], v[100:101] op_sel_hi:[1,0]
	v_pk_mul_f32 v[68:69], v[68:69], v[100:101] op_sel_hi:[1,0]
	v_pk_mul_f32 v[66:67], v[66:67], v[100:101] op_sel_hi:[1,0]
	v_pk_mul_f32 v[64:65], v[64:65], v[100:101] op_sel_hi:[1,0]
	v_pk_mul_f32 v[62:63], v[62:63], v[100:101] op_sel_hi:[1,0]
	v_pk_mul_f32 v[60:61], v[60:61], v[100:101] op_sel_hi:[1,0]
	v_pk_mul_f32 v[58:59], v[58:59], v[100:101] op_sel_hi:[1,0]
	v_pk_mul_f32 v[56:57], v[56:57], v[100:101] op_sel_hi:[1,0]
	v_pk_mul_f32 v[54:55], v[54:55], v[100:101] op_sel_hi:[1,0]
	v_pk_mul_f32 v[52:53], v[52:53], v[100:101] op_sel_hi:[1,0]
	v_pk_mul_f32 v[50:51], v[50:51], v[100:101] op_sel_hi:[1,0]
	v_pk_mul_f32 v[48:49], v[48:49], v[100:101] op_sel_hi:[1,0]

; __device__ __forceinline__ float max3f(float a, float b, float c) { return fmaxf(fmaxf(a, b), c); }
; __device__ __forceinline__ float max2f(float a, float b) { return fmaxf(a, b); }
; __device__ __forceinline__ void softmax_head(f32x16& s, int kb, int lq, int radius, bool full, int hi, HState& S) {
;     ...
;     float t0 = max3f(s[0], s[1], s[2]), t1 = max3f(s[3], s[4], s[5]);
;     t0 = max3f(t0, s[6], s[7]); t1 = max3f(t1, s[8], s[9]); t0 = max3f(t0, s[10], s[11]); t1 = max3f(t1, s[12], s[13]);
;     float tmax = max3f(t0, s[14], s[15]); tmax = max2f(tmax, t1);
;     { auto rr = __builtin_amdgcn_permlane32_swap(__float_as_uint(tmax), __float_as_uint(tmax), false, false); tmax = max2f(__uint_as_float(rr[0]), __uint_as_float(rr[1])); }
;     if (__builtin_amdgcn_ballot_w64(tmax > S.m + 8.0f) != 0ull) {
;         const float mn = max2f(S.m, tmax), alpha = __builtin_amdgcn_exp2f(S.m - mn); S.m = mn; S.l *= alpha;
; #pragma unroll
;         for (int dh = 0; dh < 2; ++dh)
; #pragma unroll
;             for (int r = 0; r < 16; ++r) S.o[dh][r] *= alpha;
;     }
; __device__ __forceinline__ void softmax_tail(f32x16& s, HState& S, u32x4 (&pw)[2]) {
;     ...
;     float p0 = s[0], p1 = s[1];
; #pragma unroll
;     for (int r = 2; r < 16; r += 2) { p0 += s[r]; p1 += s[r + 1]; }
;     S.l += p0 + p1;
.LBB0_436:
	v_add_f32_e32 v0, v15, v219
	v_add_f32_e32 v15, v218, v220
	v_add_f32_e32 v0, v221, v0
	v_add_f32_e32 v15, v222, v15
	v_add_f32_e32 v0, v223, v0
	v_add_f32_e32 v15, v224, v15
	v_add_f32_e32 v0, v225, v0
	v_add_f32_e32 v15, v226, v15
	v_add_f32_e32 v0, v227, v0
	v_add_f32_e32 v15, v228, v15
	v_add_f32_e32 v0, v229, v0
	v_add_f32_e32 v15, v230, v15
	v_add_f32_e32 v0, v231, v0
	v_add_f32_e32 v15, v232, v15
	v_add_f32_e32 v0, v0, v15
	v_max_f32_e32 v15, v96, v97
	v_max3_f32 v148, v99, v100, v101
	v_max3_f32 v15, v15, v98, v102
	v_max3_f32 v148, v148, v104, v105
	v_max3_f32 v15, v15, v103, v106
	v_max3_f32 v148, v148, v108, v109
	v_max3_f32 v15, v15, v107, v110
	v_max3_f32 v15, v15, v111, v148
	v_mov_b32_e32 v148, v15
	s_nop 1
	v_permlane32_swap_b32_e32 v15, v148
	v_max_f32_e32 v15, v15, v148
	v_add_f32_e32 v148, 0x41000000, v183
	v_add_f32_e32 v0, v185, v0
	v_cmp_gt_f32_e32 vcc, v15, v148
	s_cbranch_vccz .LBB0_438
	v_max_f32_e32 v15, v15, v15
	v_max_f32_e32 v148, v183, v183
	v_max_f32_e32 v15, v148, v15
	v_sub_f32_e32 v148, v183, v15
	v_exp_f32_e32 v148, v148
	v_mov_b32_e32 v183, v15
	v_mul_f32_e32 v0, v0, v148
	v_pk_mul_f32 v[46:47], v[46:47], v[148:149] op_sel_hi:[1,0]
	v_pk_mul_f32 v[44:45], v[44:45], v[148:149] op_sel_hi:[1,0]
	v_pk_mul_f32 v[42:43], v[42:43], v[148:149] op_sel_hi:[1,0]
	v_pk_mul_f32 v[40:41], v[40:41], v[148:149] op_sel_hi:[1,0]
	v_pk_mul_f32 v[38:39], v[38:39], v[148:149] op_sel_hi:[1,0]
	v_pk_mul_f32 v[36:37], v[36:37], v[148:149] op_sel_hi:[1,0]
	v_pk_mul_f32 v[34:35], v[34:35], v[148:149] op_sel_hi:[1,0]
	v_pk_mul_f32 v[32:33], v[32:33], v[148:149] op_sel_hi:[1,0]
	v_pk_mul_f32 v[30:31], v[30:31], v[148:149] op_sel_hi:[1,0]
	v_pk_mul_f32 v[28:29], v[28:29], v[148:149] op_sel_hi:[1,0]
	v_pk_mul_f32 v[26:27], v[26:27], v[148:149] op_sel_hi:[1,0]
	v_pk_mul_f32 v[24:25], v[24:25], v[148:149] op_sel_hi:[1,0]
	v_pk_mul_f32 v[22:23], v[22:23], v[148:149] op_sel_hi:[1,0]
	v_pk_mul_f32 v[20:21], v[20:21], v[148:149] op_sel_hi:[1,0]
	v_pk_mul_f32 v[18:19], v[18:19], v[148:149] op_sel_hi:[1,0]
	v_pk_mul_f32 v[16:17], v[16:17], v[148:149] op_sel_hi:[1,0]

; __device__ __forceinline__ float max3f(float a, float b, float c) { return fmaxf(fmaxf(a, b), c); }
; __device__ __forceinline__ float max2f(float a, float b) { return fmaxf(a, b); }
; __device__ __forceinline__ void softmax_head(f32x16& s, int kb, int lq, int radius, bool full, int hi, HState& S) {
;     ...
;     float t0 = max3f(s[0], s[1], s[2]), t1 = max3f(s[3], s[4], s[5]);
;     t0 = max3f(t0, s[6], s[7]); t1 = max3f(t1, s[8], s[9]); t0 = max3f(t0, s[10], s[11]); t1 = max3f(t1, s[12], s[13]);
;     float tmax = max3f(t0, s[14], s[15]); tmax = max2f(tmax, t1);
;     { auto rr = __builtin_amdgcn_permlane32_swap(__float_as_uint(tmax), __float_as_uint(tmax), false, false); tmax = max2f(__uint_as_float(rr[0]), __uint_as_float(rr[1])); }
;     if (__builtin_amdgcn_ballot_w64(tmax > S.m + 8.0f) != 0ull) {
;         const float mn = max2f(S.m, tmax), alpha = __builtin_amdgcn_exp2f(S.m - mn); S.m = mn; S.l *= alpha;
; #pragma unroll
;         for (int dh = 0; dh < 2; ++dh)
; #pragma unroll
;             for (int r = 0; r < 16; ++r) S.o[dh][r] *= alpha;
;     }
.LBB0_445:
	s_nop 10
	v_max_f32_e32 v100, v80, v81
	v_max3_f32 v101, v83, v84, v85
	v_max3_f32 v100, v100, v82, v86
	v_max3_f32 v101, v101, v88, v89
	v_max3_f32 v100, v100, v87, v90
	v_max3_f32 v101, v101, v92, v93
	v_max3_f32 v100, v100, v91, v94
	v_max3_f32 v100, v100, v95, v101
	v_mov_b32_e32 v101, v100
	s_nop 1
	v_permlane32_swap_b32_e32 v100, v101
	v_max_f32_e32 v100, v100, v101
	v_add_f32_e32 v101, 0x41000000, v184
	v_cmp_gt_f32_e32 vcc, v100, v101
	s_cbranch_vccz .LBB0_447
	v_max_f32_e32 v100, v100, v100
	v_max_f32_e32 v101, v184, v184
	v_max_f32_e32 v101, v101, v100
	v_sub_f32_e32 v100, v184, v101
	v_exp_f32_e32 v100, v100
	v_mov_b32_e32 v184, v101
	v_mul_f32_e32 v197, v197, v100
	v_pk_mul_f32 v[78:79], v[78:79], v[100:101] op_sel_hi:[1,0]
	v_pk_mul_f32 v[76:77], v[76:77], v[100:101] op_sel_hi:[1,0]
	v_pk_mul_f32 v[74:75], v[74:75], v[100:101] op_sel_hi:[1,0]
	v_pk_mul_f32 v[72:73], v[72:73], v[100:101] op_sel_hi:[1,0]
	v_pk_mul_f32 v[70:71], v[70:71], v[100:101] op_sel_hi:[1,0]
	v_pk_mul_f32 v[68:69], v[68:69], v[100:101] op_sel_hi:[1,0]
	v_pk_mul_f32 v[66:67], v[66:67], v[100:101] op_sel_hi:[1,0]
	v_pk_mul_f32 v[64:65], v[64:65], v[100:101] op_sel_hi:[1,0]
	v_pk_mul_f32 v[62:63], v[62:63], v[100:101] op_sel_hi:[1,0]
	v_pk_mul_f32 v[60:61], v[60:61], v[100:101] op_sel_hi:[1,0]
	v_pk_mul_f32 v[58:59], v[58:59], v[100:101] op_sel_hi:[1,0]
	v_pk_mul_f32 v[56:57], v[56:57], v[100:101] op_sel_hi:[1,0]
	v_pk_mul_f32 v[54:55], v[54:55], v[100:101] op_sel_hi:[1,0]
	v_pk_mul_f32 v[52:53], v[52:53], v[100:101] op_sel_hi:[1,0]
	v_pk_mul_f32 v[50:51], v[50:51], v[100:101] op_sel_hi:[1,0]
	v_pk_mul_f32 v[48:49], v[48:49], v[100:101] op_sel_hi:[1,0]

; __device__ __forceinline__ float max3f(float a, float b, float c) { return fmaxf(fmaxf(a, b), c); }
; __device__ __forceinline__ float max2f(float a, float b) { return fmaxf(a, b); }
; __device__ __forceinline__ void softmax_head(f32x16& s, int kb, int lq, int radius, bool full, int hi, HState& S) {
;     ...
;     float t0 = max3f(s[0], s[1], s[2]), t1 = max3f(s[3], s[4], s[5]);
;     t0 = max3f(t0, s[6], s[7]); t1 = max3f(t1, s[8], s[9]); t0 = max3f(t0, s[10], s[11]); t1 = max3f(t1, s[12], s[13]);
;     float tmax = max3f(t0, s[14], s[15]); tmax = max2f(tmax, t1);
;     { auto rr = __builtin_amdgcn_permlane32_swap(__float_as_uint(tmax), __float_as_uint(tmax), false, false); tmax = max2f(__uint_as_float(rr[0]), __uint_as_float(rr[1])); }
;     if (__builtin_amdgcn_ballot_w64(tmax > S.m + 8.0f) != 0ull) {
;         const float mn = max2f(S.m, tmax), alpha = __builtin_amdgcn_exp2f(S.m - mn); S.m = mn; S.l *= alpha;
; #pragma unroll
;         for (int dh = 0; dh < 2; ++dh)
; #pragma unroll
;             for (int r = 0; r < 16; ++r) S.o[dh][r] *= alpha;
;     }
.LBB0_449:
	s_nop 9
	v_max_f32_e32 v14, v96, v97
	v_max3_f32 v15, v99, v100, v101
	v_max3_f32 v14, v14, v98, v102
	v_max3_f32 v15, v15, v104, v105
	v_max3_f32 v14, v14, v103, v106
	v_max3_f32 v15, v15, v108, v109
	v_max3_f32 v14, v14, v107, v110
	v_max3_f32 v14, v14, v111, v15
	v_mov_b32_e32 v15, v14
	s_nop 1
	v_permlane32_swap_b32_e32 v14, v15
	v_max_f32_e32 v14, v14, v15
	v_add_f32_e32 v15, 0x41000000, v183
	v_cmp_gt_f32_e32 vcc, v14, v15
	s_cbranch_vccz .LBB0_451
	v_max_f32_e32 v14, v14, v14
	v_max_f32_e32 v15, v183, v183
	v_max_f32_e32 v15, v15, v14
	v_sub_f32_e32 v14, v183, v15
	v_exp_f32_e32 v14, v14
	v_mov_b32_e32 v183, v15
	v_mul_f32_e32 v185, v185, v14
	v_pk_mul_f32 v[46:47], v[46:47], v[14:15] op_sel_hi:[1,0]
	v_pk_mul_f32 v[44:45], v[44:45], v[14:15] op_sel_hi:[1,0]
	v_pk_mul_f32 v[42:43], v[42:43], v[14:15] op_sel_hi:[1,0]
	v_pk_mul_f32 v[40:41], v[40:41], v[14:15] op_sel_hi:[1,0]
	v_pk_mul_f32 v[38:39], v[38:39], v[14:15] op_sel_hi:[1,0]
	v_pk_mul_f32 v[36:37], v[36:37], v[14:15] op_sel_hi:[1,0]
	v_pk_mul_f32 v[34:35], v[34:35], v[14:15] op_sel_hi:[1,0]
	v_pk_mul_f32 v[32:33], v[32:33], v[14:15] op_sel_hi:[1,0]
	v_pk_mul_f32 v[30:31], v[30:31], v[14:15] op_sel_hi:[1,0]
	v_pk_mul_f32 v[28:29], v[28:29], v[14:15] op_sel_hi:[1,0]
	v_pk_mul_f32 v[26:27], v[26:27], v[14:15] op_sel_hi:[1,0]
	v_pk_mul_f32 v[24:25], v[24:25], v[14:15] op_sel_hi:[1,0]
	v_pk_mul_f32 v[22:23], v[22:23], v[14:15] op_sel_hi:[1,0]
	v_pk_mul_f32 v[20:21], v[20:21], v[14:15] op_sel_hi:[1,0]
	v_pk_mul_f32 v[18:19], v[18:19], v[14:15] op_sel_hi:[1,0]
	v_pk_mul_f32 v[16:17], v[16:17], v[14:15] op_sel_hi:[1,0]

; __device__ __forceinline__ float max3f(float a, float b, float c) { return fmaxf(fmaxf(a, b), c); }
; __device__ __forceinline__ float max2f(float a, float b) { return fmaxf(a, b); }
; __device__ __forceinline__ void softmax_head(f32x16& s, int kb, int lq, int radius, bool full, int hi, HState& S) {
;     ...
;     float t0 = max3f(s[0], s[1], s[2]), t1 = max3f(s[3], s[4], s[5]);
;     t0 = max3f(t0, s[6], s[7]); t1 = max3f(t1, s[8], s[9]); t0 = max3f(t0, s[10], s[11]); t1 = max3f(t1, s[12], s[13]);
;     float tmax = max3f(t0, s[14], s[15]); tmax = max2f(tmax, t1);
;     { auto rr = __builtin_amdgcn_permlane32_swap(__float_as_uint(tmax), __float_as_uint(tmax), false, false); tmax = max2f(__uint_as_float(rr[0]), __uint_as_float(rr[1])); }
;     if (__builtin_amdgcn_ballot_w64(tmax > S.m + 8.0f) != 0ull) {
;         const float mn = max2f(S.m, tmax), alpha = __builtin_amdgcn_exp2f(S.m - mn); S.m = mn; S.l *= alpha;
; #pragma unroll
;         for (int dh = 0; dh < 2; ++dh)
; #pragma unroll
;             for (int r = 0; r < 16; ++r) S.o[dh][r] *= alpha;
;     }
.LBB0_519:
	s_nop 6
	v_max_f32_e32 v100, v80, v81
	v_max3_f32 v101, v83, v84, v85
	v_max3_f32 v100, v100, v82, v86
	v_max3_f32 v101, v101, v88, v89
	v_max3_f32 v100, v100, v87, v90
	v_max3_f32 v101, v101, v92, v93
	v_max3_f32 v100, v100, v91, v94
	v_max3_f32 v100, v100, v95, v101
	v_mov_b32_e32 v101, v100
	s_nop 1
	v_permlane32_swap_b32_e32 v100, v101
	v_max_f32_e32 v100, v100, v101
	v_add_f32_e32 v101, 0x41000000, v168
	v_cmp_gt_f32_e32 vcc, v100, v101
	s_cbranch_vccz .LBB0_521
	v_max_f32_e32 v100, v100, v100
	v_max_f32_e32 v101, v168, v168
	v_max_f32_e32 v101, v101, v100
	v_sub_f32_e32 v100, v168, v101
	v_exp_f32_e32 v100, v100
	v_mov_b32_e32 v168, v101
	v_mul_f32_e32 v175, v175, v100
	v_pk_mul_f32 v[78:79], v[78:79], v[100:101] op_sel_hi:[1,0]
	v_pk_mul_f32 v[76:77], v[76:77], v[100:101] op_sel_hi:[1,0]
	v_pk_mul_f32 v[74:75], v[74:75], v[100:101] op_sel_hi:[1,0]
	v_pk_mul_f32 v[72:73], v[72:73], v[100:101] op_sel_hi:[1,0]
	v_pk_mul_f32 v[70:71], v[70:71], v[100:101] op_sel_hi:[1,0]
	v_pk_mul_f32 v[68:69], v[68:69], v[100:101] op_sel_hi:[1,0]
	v_pk_mul_f32 v[66:67], v[66:67], v[100:101] op_sel_hi:[1,0]
	v_pk_mul_f32 v[64:65], v[64:65], v[100:101] op_sel_hi:[1,0]
	v_pk_mul_f32 v[62:63], v[62:63], v[100:101] op_sel_hi:[1,0]
	v_pk_mul_f32 v[60:61], v[60:61], v[100:101] op_sel_hi:[1,0]
	v_pk_mul_f32 v[58:59], v[58:59], v[100:101] op_sel_hi:[1,0]
	v_pk_mul_f32 v[56:57], v[56:57], v[100:101] op_sel_hi:[1,0]
	v_pk_mul_f32 v[54:55], v[54:55], v[100:101] op_sel_hi:[1,0]
	v_pk_mul_f32 v[52:53], v[52:53], v[100:101] op_sel_hi:[1,0]
	v_pk_mul_f32 v[50:51], v[50:51], v[100:101] op_sel_hi:[1,0]
	v_pk_mul_f32 v[48:49], v[48:49], v[100:101] op_sel_hi:[1,0]

; __device__ __forceinline__ float max3f(float a, float b, float c) { return fmaxf(fmaxf(a, b), c); }
; __device__ __forceinline__ float max2f(float a, float b) { return fmaxf(a, b); }
; __device__ __forceinline__ void softmax_head(f32x16& s, int kb, int lq, int radius, bool full, int hi, HState& S) {
;     ...
;     float t0 = max3f(s[0], s[1], s[2]), t1 = max3f(s[3], s[4], s[5]);
;     t0 = max3f(t0, s[6], s[7]); t1 = max3f(t1, s[8], s[9]); t0 = max3f(t0, s[10], s[11]); t1 = max3f(t1, s[12], s[13]);
;     float tmax = max3f(t0, s[14], s[15]); tmax = max2f(tmax, t1);
;     { auto rr = __builtin_amdgcn_permlane32_swap(__float_as_uint(tmax), __float_as_uint(tmax), false, false); tmax = max2f(__uint_as_float(rr[0]), __uint_as_float(rr[1])); }
;     if (__builtin_amdgcn_ballot_w64(tmax > S.m + 8.0f) != 0ull) {
;         const float mn = max2f(S.m, tmax), alpha = __builtin_amdgcn_exp2f(S.m - mn); S.m = mn; S.l *= alpha;
; #pragma unroll
;         for (int dh = 0; dh < 2; ++dh)
; #pragma unroll
;             for (int r = 0; r < 16; ++r) S.o[dh][r] *= alpha;
;     }
.LBB0_523:
	s_nop 9
	v_max_f32_e32 v15, v96, v97
	v_max3_f32 v148, v99, v100, v101
	v_max3_f32 v15, v15, v98, v102
	v_max3_f32 v148, v148, v104, v105
	v_max3_f32 v15, v15, v103, v106
	v_max3_f32 v148, v148, v108, v109
	v_max3_f32 v15, v15, v107, v110
	v_max3_f32 v15, v15, v111, v148
	v_mov_b32_e32 v148, v15
	s_nop 1
	v_permlane32_swap_b32_e32 v15, v148
	v_max_f32_e32 v15, v15, v148
	v_add_f32_e32 v148, 0x41000000, v169
	v_cmp_gt_f32_e32 vcc, v15, v148
	s_cbranch_vccz .LBB0_525
	v_max_f32_e32 v15, v15, v15
	v_max_f32_e32 v148, v169, v169
	v_max_f32_e32 v15, v148, v15
	v_sub_f32_e32 v148, v169, v15
	v_exp_f32_e32 v148, v148
	v_mov_b32_e32 v169, v15
	v_mul_f32_e32 v176, v176, v148
	v_pk_mul_f32 v[46:47], v[46:47], v[148:149] op_sel_hi:[1,0]
	v_pk_mul_f32 v[44:45], v[44:45], v[148:149] op_sel_hi:[1,0]
	v_pk_mul_f32 v[42:43], v[42:43], v[148:149] op_sel_hi:[1,0]
	v_pk_mul_f32 v[40:41], v[40:41], v[148:149] op_sel_hi:[1,0]
	v_pk_mul_f32 v[38:39], v[38:39], v[148:149] op_sel_hi:[1,0]
	v_pk_mul_f32 v[36:37], v[36:37], v[148:149] op_sel_hi:[1,0]
	v_pk_mul_f32 v[34:35], v[34:35], v[148:149] op_sel_hi:[1,0]
	v_pk_mul_f32 v[32:33], v[32:33], v[148:149] op_sel_hi:[1,0]
	v_pk_mul_f32 v[30:31], v[30:31], v[148:149] op_sel_hi:[1,0]
	v_pk_mul_f32 v[28:29], v[28:29], v[148:149] op_sel_hi:[1,0]
	v_pk_mul_f32 v[26:27], v[26:27], v[148:149] op_sel_hi:[1,0]
	v_pk_mul_f32 v[24:25], v[24:25], v[148:149] op_sel_hi:[1,0]
	v_pk_mul_f32 v[22:23], v[22:23], v[148:149] op_sel_hi:[1,0]
	v_pk_mul_f32 v[20:21], v[20:21], v[148:149] op_sel_hi:[1,0]
	v_pk_mul_f32 v[18:19], v[18:19], v[148:149] op_sel_hi:[1,0]
	v_pk_mul_f32 v[16:17], v[16:17], v[148:149] op_sel_hi:[1,0]

; __device__ __forceinline__ float max3f(float a, float b, float c) { return fmaxf(fmaxf(a, b), c); }
; __device__ __forceinline__ float max2f(float a, float b) { return fmaxf(a, b); }
; __device__ __forceinline__ void softmax_head(f32x16& s, int kb, int lq, int radius, bool full, int hi, HState& S) {
;     ...
;     float t0 = max3f(s[0], s[1], s[2]), t1 = max3f(s[3], s[4], s[5]);
;     t0 = max3f(t0, s[6], s[7]); t1 = max3f(t1, s[8], s[9]); t0 = max3f(t0, s[10], s[11]); t1 = max3f(t1, s[12], s[13]);
;     float tmax = max3f(t0, s[14], s[15]); tmax = max2f(tmax, t1);
;     { auto rr = __builtin_amdgcn_permlane32_swap(__float_as_uint(tmax), __float_as_uint(tmax), false, false); tmax = max2f(__uint_as_float(rr[0]), __uint_as_float(rr[1])); }
;     if (__builtin_amdgcn_ballot_w64(tmax > S.m + 8.0f) != 0ull) {
;         const float mn = max2f(S.m, tmax), alpha = __builtin_amdgcn_exp2f(S.m - mn); S.m = mn; S.l *= alpha;
; #pragma unroll
;         for (int dh = 0; dh < 2; ++dh)
; #pragma unroll
;             for (int r = 0; r < 16; ++r) S.o[dh][r] *= alpha;
;     }
; __device__ __forceinline__ void softmax_tail(f32x16& s, HState& S, u32x4 (&pw)[2]) {
;     ...
;     float p0 = s[0], p1 = s[1];
; #pragma unroll
;     for (int r = 2; r < 16; r += 2) { p0 += s[r]; p1 += s[r + 1]; }
;     S.l += p0 + p1;
.LBB0_527:
	v_add_f32_e32 v14, v201, v222
	v_add_f32_e32 v100, v203, v223
	v_add_f32_e32 v14, v224, v14
	v_add_f32_e32 v100, v225, v100
	v_add_f32_e32 v14, v226, v14
	v_add_f32_e32 v100, v227, v100
	v_add_f32_e32 v14, v228, v14
	v_add_f32_e32 v100, v229, v100
	v_add_f32_e32 v14, v230, v14
	v_add_f32_e32 v100, v231, v100
	v_add_f32_e32 v14, v232, v14
	v_add_f32_e32 v100, v233, v100
	v_add_f32_e32 v14, v234, v14
	v_add_f32_e32 v100, v235, v100
	v_add_f32_e32 v14, v14, v100
	v_max_f32_e32 v100, v80, v81
	v_max3_f32 v101, v83, v84, v85
	v_max3_f32 v100, v100, v82, v86
	v_max3_f32 v101, v101, v88, v89
	v_max3_f32 v100, v100, v87, v90
	v_max3_f32 v101, v101, v92, v93
	v_max3_f32 v100, v100, v91, v94
	v_max3_f32 v100, v100, v95, v101
	v_mov_b32_e32 v101, v100
	s_nop 1
	v_permlane32_swap_b32_e32 v100, v101
	v_max_f32_e32 v100, v100, v101
	v_add_f32_e32 v101, 0x41000000, v168
	v_add_f32_e32 v14, v175, v14
	v_cmp_gt_f32_e32 vcc, v100, v101
	s_cbranch_vccz .LBB0_529
	v_max_f32_e32 v100, v100, v100
	v_max_f32_e32 v101, v168, v168
	v_max_f32_e32 v101, v101, v100
	v_sub_f32_e32 v100, v168, v101
	v_exp_f32_e32 v100, v100
	v_mov_b32_e32 v168, v101
	v_mul_f32_e32 v14, v14, v100
	v_pk_mul_f32 v[78:79], v[78:79], v[100:101] op_sel_hi:[1,0]
	v_pk_mul_f32 v[76:77], v[76:77], v[100:101] op_sel_hi:[1,0]
	v_pk_mul_f32 v[74:75], v[74:75], v[100:101] op_sel_hi:[1,0]
	v_pk_mul_f32 v[72:73], v[72:73], v[100:101] op_sel_hi:[1,0]
	v_pk_mul_f32 v[70:71], v[70:71], v[100:101] op_sel_hi:[1,0]
	v_pk_mul_f32 v[68:69], v[68:69], v[100:101] op_sel_hi:[1,0]
	v_pk_mul_f32 v[66:67], v[66:67], v[100:101] op_sel_hi:[1,0]
	v_pk_mul_f32 v[64:65], v[64:65], v[100:101] op_sel_hi:[1,0]
	v_pk_mul_f32 v[62:63], v[62:63], v[100:101] op_sel_hi:[1,0]
	v_pk_mul_f32 v[60:61], v[60:61], v[100:101] op_sel_hi:[1,0]
	v_pk_mul_f32 v[58:59], v[58:59], v[100:101] op_sel_hi:[1,0]
	v_pk_mul_f32 v[56:57], v[56:57], v[100:101] op_sel_hi:[1,0]
	v_pk_mul_f32 v[54:55], v[54:55], v[100:101] op_sel_hi:[1,0]
	v_pk_mul_f32 v[52:53], v[52:53], v[100:101] op_sel_hi:[1,0]
	v_pk_mul_f32 v[50:51], v[50:51], v[100:101] op_sel_hi:[1,0]
	v_pk_mul_f32 v[48:49], v[48:49], v[100:101] op_sel_hi:[1,0]

; __device__ __forceinline__ float max3f(float a, float b, float c) { return fmaxf(fmaxf(a, b), c); }
; __device__ __forceinline__ float max2f(float a, float b) { return fmaxf(a, b); }
; __device__ __forceinline__ void softmax_head(f32x16& s, int kb, int lq, int radius, bool full, int hi, HState& S) {
;     ...
;     float t0 = max3f(s[0], s[1], s[2]), t1 = max3f(s[3], s[4], s[5]);
;     t0 = max3f(t0, s[6], s[7]); t1 = max3f(t1, s[8], s[9]); t0 = max3f(t0, s[10], s[11]); t1 = max3f(t1, s[12], s[13]);
;     float tmax = max3f(t0, s[14], s[15]); tmax = max2f(tmax, t1);
;     { auto rr = __builtin_amdgcn_permlane32_swap(__float_as_uint(tmax), __float_as_uint(tmax), false, false); tmax = max2f(__uint_as_float(rr[0]), __uint_as_float(rr[1])); }
;     if (__builtin_amdgcn_ballot_w64(tmax > S.m + 8.0f) != 0ull) {
;         const float mn = max2f(S.m, tmax), alpha = __builtin_amdgcn_exp2f(S.m - mn); S.m = mn; S.l *= alpha;
; #pragma unroll
;         for (int dh = 0; dh < 2; ++dh)
; #pragma unroll
;             for (int r = 0; r < 16; ++r) S.o[dh][r] *= alpha;
;     }
; __device__ __forceinline__ void softmax_tail(f32x16& s, HState& S, u32x4 (&pw)[2]) {
;     ...
;     float p0 = s[0], p1 = s[1];
; #pragma unroll
;     for (int r = 2; r < 16; r += 2) { p0 += s[r]; p1 += s[r + 1]; }
;     S.l += p0 + p1;
.LBB0_531:
	v_add_f32_e32 v0, v15, v208
	v_add_f32_e32 v15, v173, v209
	v_add_f32_e32 v0, v210, v0
	v_add_f32_e32 v15, v211, v15
	v_add_f32_e32 v0, v212, v0
	v_add_f32_e32 v15, v213, v15
	v_add_f32_e32 v0, v214, v0
	v_add_f32_e32 v15, v215, v15
	v_add_f32_e32 v0, v216, v0
	v_add_f32_e32 v15, v217, v15
	v_add_f32_e32 v0, v218, v0
	v_add_f32_e32 v15, v219, v15
	v_add_f32_e32 v0, v220, v0
	v_add_f32_e32 v15, v221, v15
	v_add_f32_e32 v0, v0, v15
	v_max_f32_e32 v15, v96, v97
	v_max3_f32 v148, v99, v100, v101
	v_max3_f32 v15, v15, v98, v102
	v_max3_f32 v148, v148, v104, v105
	v_max3_f32 v15, v15, v103, v106
	v_max3_f32 v148, v148, v108, v109
	v_max3_f32 v15, v15, v107, v110
	v_max3_f32 v15, v15, v111, v148
	v_mov_b32_e32 v148, v15
	s_nop 1
	v_permlane32_swap_b32_e32 v15, v148
	v_max_f32_e32 v15, v15, v148
	v_add_f32_e32 v148, 0x41000000, v169
	v_add_f32_e32 v0, v176, v0
	v_cmp_gt_f32_e32 vcc, v15, v148
	s_cbranch_vccz .LBB0_533
	v_max_f32_e32 v15, v15, v15
	v_max_f32_e32 v148, v169, v169
	v_max_f32_e32 v15, v148, v15
	v_sub_f32_e32 v148, v169, v15
	v_exp_f32_e32 v148, v148
	v_mov_b32_e32 v169, v15
	v_mul_f32_e32 v0, v0, v148
	v_pk_mul_f32 v[46:47], v[46:47], v[148:149] op_sel_hi:[1,0]
	v_pk_mul_f32 v[44:45], v[44:45], v[148:149] op_sel_hi:[1,0]
	v_pk_mul_f32 v[42:43], v[42:43], v[148:149] op_sel_hi:[1,0]
	v_pk_mul_f32 v[40:41], v[40:41], v[148:149] op_sel_hi:[1,0]
	v_pk_mul_f32 v[38:39], v[38:39], v[148:149] op_sel_hi:[1,0]
	v_pk_mul_f32 v[36:37], v[36:37], v[148:149] op_sel_hi:[1,0]
	v_pk_mul_f32 v[34:35], v[34:35], v[148:149] op_sel_hi:[1,0]
	v_pk_mul_f32 v[32:33], v[32:33], v[148:149] op_sel_hi:[1,0]
	v_pk_mul_f32 v[30:31], v[30:31], v[148:149] op_sel_hi:[1,0]
	v_pk_mul_f32 v[28:29], v[28:29], v[148:149] op_sel_hi:[1,0]
	v_pk_mul_f32 v[26:27], v[26:27], v[148:149] op_sel_hi:[1,0]
	v_pk_mul_f32 v[24:25], v[24:25], v[148:149] op_sel_hi:[1,0]
	v_pk_mul_f32 v[22:23], v[22:23], v[148:149] op_sel_hi:[1,0]
	v_pk_mul_f32 v[20:21], v[20:21], v[148:149] op_sel_hi:[1,0]
	v_pk_mul_f32 v[18:19], v[18:19], v[148:149] op_sel_hi:[1,0]
	v_pk_mul_f32 v[16:17], v[16:17], v[148:149] op_sel_hi:[1,0]

; __device__ __forceinline__ float max3f(float a, float b, float c) { return fmaxf(fmaxf(a, b), c); }
; __device__ __forceinline__ float max2f(float a, float b) { return fmaxf(a, b); }
; __device__ __forceinline__ void softmax_head(f32x16& s, int kb, int lq, int radius, bool full, int hi, HState& S) {
;     ...
;     float t0 = max3f(s[0], s[1], s[2]), t1 = max3f(s[3], s[4], s[5]);
;     t0 = max3f(t0, s[6], s[7]); t1 = max3f(t1, s[8], s[9]); t0 = max3f(t0, s[10], s[11]); t1 = max3f(t1, s[12], s[13]);
;     float tmax = max3f(t0, s[14], s[15]); tmax = max2f(tmax, t1);
;     { auto rr = __builtin_amdgcn_permlane32_swap(__float_as_uint(tmax), __float_as_uint(tmax), false, false); tmax = max2f(__uint_as_float(rr[0]), __uint_as_float(rr[1])); }
;     if (__builtin_amdgcn_ballot_w64(tmax > S.m + 8.0f) != 0ull) {
;         const float mn = max2f(S.m, tmax), alpha = __builtin_amdgcn_exp2f(S.m - mn); S.m = mn; S.l *= alpha;
; #pragma unroll
;         for (int dh = 0; dh < 2; ++dh)
; #pragma unroll
;             for (int r = 0; r < 16; ++r) S.o[dh][r] *= alpha;
;     }
.LBB0_539:
	s_nop 10
	v_max_f32_e32 v15, v80, v81
	v_max3_f32 v100, v83, v84, v85
	v_max3_f32 v15, v15, v82, v86
	v_max3_f32 v100, v100, v88, v89
	v_max3_f32 v15, v15, v87, v90
	v_max3_f32 v100, v100, v92, v93
	v_max3_f32 v15, v15, v91, v94
	v_max3_f32 v15, v15, v95, v100
	v_mov_b32_e32 v100, v15
	s_nop 1
	v_permlane32_swap_b32_e32 v15, v100
	v_max_f32_e32 v15, v15, v100
	v_add_f32_e32 v100, 0x41000000, v168
	v_cmp_gt_f32_e32 vcc, v15, v100
	s_cbranch_vccz .LBB0_541
	v_max_f32_e32 v15, v15, v15
	v_max_f32_e32 v100, v168, v168
	v_max_f32_e32 v15, v100, v15
	v_sub_f32_e32 v100, v168, v15
	v_exp_f32_e32 v100, v100
	v_mov_b32_e32 v168, v15
	v_mul_f32_e32 v175, v175, v100
	v_pk_mul_f32 v[78:79], v[78:79], v[100:101] op_sel_hi:[1,0]
	v_pk_mul_f32 v[76:77], v[76:77], v[100:101] op_sel_hi:[1,0]
	v_pk_mul_f32 v[74:75], v[74:75], v[100:101] op_sel_hi:[1,0]
	v_pk_mul_f32 v[72:73], v[72:73], v[100:101] op_sel_hi:[1,0]
	v_pk_mul_f32 v[70:71], v[70:71], v[100:101] op_sel_hi:[1,0]
	v_pk_mul_f32 v[68:69], v[68:69], v[100:101] op_sel_hi:[1,0]
	v_pk_mul_f32 v[66:67], v[66:67], v[100:101] op_sel_hi:[1,0]
	v_pk_mul_f32 v[64:65], v[64:65], v[100:101] op_sel_hi:[1,0]
	v_pk_mul_f32 v[62:63], v[62:63], v[100:101] op_sel_hi:[1,0]
	v_pk_mul_f32 v[60:61], v[60:61], v[100:101] op_sel_hi:[1,0]
	v_pk_mul_f32 v[58:59], v[58:59], v[100:101] op_sel_hi:[1,0]
	v_pk_mul_f32 v[56:57], v[56:57], v[100:101] op_sel_hi:[1,0]
	v_pk_mul_f32 v[54:55], v[54:55], v[100:101] op_sel_hi:[1,0]
	v_pk_mul_f32 v[52:53], v[52:53], v[100:101] op_sel_hi:[1,0]
	v_pk_mul_f32 v[50:51], v[50:51], v[100:101] op_sel_hi:[1,0]
	v_pk_mul_f32 v[48:49], v[48:49], v[100:101] op_sel_hi:[1,0]

; __device__ __forceinline__ float max3f(float a, float b, float c) { return fmaxf(fmaxf(a, b), c); }
; __device__ __forceinline__ float max2f(float a, float b) { return fmaxf(a, b); }
; __device__ __forceinline__ void softmax_head(f32x16& s, int kb, int lq, int radius, bool full, int hi, HState& S) {
;     ...
;     float t0 = max3f(s[0], s[1], s[2]), t1 = max3f(s[3], s[4], s[5]);
;     t0 = max3f(t0, s[6], s[7]); t1 = max3f(t1, s[8], s[9]); t0 = max3f(t0, s[10], s[11]); t1 = max3f(t1, s[12], s[13]);
;     float tmax = max3f(t0, s[14], s[15]); tmax = max2f(tmax, t1);
;     { auto rr = __builtin_amdgcn_permlane32_swap(__float_as_uint(tmax), __float_as_uint(tmax), false, false); tmax = max2f(__uint_as_float(rr[0]), __uint_as_float(rr[1])); }
;     if (__builtin_amdgcn_ballot_w64(tmax > S.m + 8.0f) != 0ull) {
;         const float mn = max2f(S.m, tmax), alpha = __builtin_amdgcn_exp2f(S.m - mn); S.m = mn; S.l *= alpha;
; #pragma unroll
;         for (int dh = 0; dh < 2; ++dh)
; #pragma unroll
;             for (int r = 0; r < 16; ++r) S.o[dh][r] *= alpha;
;     }
.LBB0_543:
	s_nop 9
	v_max_f32_e32 v0, v96, v97
	v_max3_f32 v14, v99, v100, v101
	v_max3_f32 v0, v0, v98, v102
	v_max3_f32 v14, v14, v104, v105
	v_max3_f32 v0, v0, v103, v106
	v_max3_f32 v14, v14, v108, v109
	v_max3_f32 v0, v0, v107, v110
	v_max3_f32 v0, v0, v111, v14
	v_mov_b32_e32 v14, v0
	s_nop 1
	v_permlane32_swap_b32_e32 v0, v14
	v_max_f32_e32 v0, v0, v14
	v_add_f32_e32 v14, 0x41000000, v169
	v_cmp_gt_f32_e32 vcc, v0, v14
	s_cbranch_vccz .LBB0_513
	v_max_f32_e32 v0, v0, v0
	v_max_f32_e32 v14, v169, v169
	v_max_f32_e32 v14, v14, v0
	v_sub_f32_e32 v0, v169, v14
	v_exp_f32_e32 v0, v0
	v_mov_b32_e32 v169, v14
	v_mul_f32_e32 v176, v176, v0
	v_pk_mul_f32 v[46:47], v[46:47], v[0:1] op_sel_hi:[1,0]
	v_pk_mul_f32 v[44:45], v[44:45], v[0:1] op_sel_hi:[1,0]
	v_pk_mul_f32 v[42:43], v[42:43], v[0:1] op_sel_hi:[1,0]
	v_pk_mul_f32 v[40:41], v[40:41], v[0:1] op_sel_hi:[1,0]
	v_pk_mul_f32 v[38:39], v[38:39], v[0:1] op_sel_hi:[1,0]
	v_pk_mul_f32 v[36:37], v[36:37], v[0:1] op_sel_hi:[1,0]
	v_pk_mul_f32 v[34:35], v[34:35], v[0:1] op_sel_hi:[1,0]
	v_pk_mul_f32 v[32:33], v[32:33], v[0:1] op_sel_hi:[1,0]
	v_pk_mul_f32 v[30:31], v[30:31], v[0:1] op_sel_hi:[1,0]
	v_pk_mul_f32 v[28:29], v[28:29], v[0:1] op_sel_hi:[1,0]
	v_pk_mul_f32 v[26:27], v[26:27], v[0:1] op_sel_hi:[1,0]
	v_pk_mul_f32 v[24:25], v[24:25], v[0:1] op_sel_hi:[1,0]
	v_pk_mul_f32 v[22:23], v[22:23], v[0:1] op_sel_hi:[1,0]
	v_pk_mul_f32 v[20:21], v[20:21], v[0:1] op_sel_hi:[1,0]
	v_pk_mul_f32 v[18:19], v[18:19], v[0:1] op_sel_hi:[1,0]
	v_pk_mul_f32 v[16:17], v[16:17], v[0:1] op_sel_hi:[1,0]
	s_branch .LBB0_513

; __device__ __forceinline__ float max3f(float a, float b, float c) { return fmaxf(fmaxf(a, b), c); }
; __device__ __forceinline__ float max2f(float a, float b) { return fmaxf(a, b); }
; __device__ __forceinline__ void softmax_head(f32x16& s, int kb, int lq, int radius, bool full, int hi, HState& S) {
;     ...
;     float t0 = max3f(s[0], s[1], s[2]), t1 = max3f(s[3], s[4], s[5]);
;     t0 = max3f(t0, s[6], s[7]); t1 = max3f(t1, s[8], s[9]); t0 = max3f(t0, s[10], s[11]); t1 = max3f(t1, s[12], s[13]);
;     float tmax = max3f(t0, s[14], s[15]); tmax = max2f(tmax, t1);
;     { auto rr = __builtin_amdgcn_permlane32_swap(__float_as_uint(tmax), __float_as_uint(tmax), false, false); tmax = max2f(__uint_as_float(rr[0]), __uint_as_float(rr[1])); }
;     if (__builtin_amdgcn_ballot_w64(tmax > S.m + 8.0f) != 0ull) {
;         const float mn = max2f(S.m, tmax), alpha = __builtin_amdgcn_exp2f(S.m - mn); S.m = mn; S.l *= alpha;
; #pragma unroll
;         for (int dh = 0; dh < 2; ++dh)
; #pragma unroll
;             for (int r = 0; r < 16; ++r) S.o[dh][r] *= alpha;
;     }
.LBB0_550:
	s_nop 10
	v_max_f32_e32 v0, v80, v81
	v_max3_f32 v15, v83, v84, v85
	v_max3_f32 v0, v0, v82, v86
	v_max3_f32 v15, v15, v88, v89
	v_max3_f32 v0, v0, v87, v90
	v_max3_f32 v15, v15, v92, v93
	v_max3_f32 v0, v0, v91, v94
	v_max3_f32 v0, v0, v95, v15
	v_mov_b32_e32 v15, v0
	s_nop 1
	v_permlane32_swap_b32_e32 v0, v15
	v_max_f32_e32 v0, v0, v15
	v_add_f32_e32 v15, 0x41000000, v196
	v_cmp_gt_f32_e32 vcc, v0, v15
	s_cbranch_vccz .LBB0_552
	v_max_f32_e32 v0, v0, v0
	v_max_f32_e32 v15, v196, v196
	v_max_f32_e32 v15, v15, v0
	v_sub_f32_e32 v0, v196, v15
	v_exp_f32_e32 v0, v0
	v_mov_b32_e32 v196, v15
	v_mul_f32_e32 v207, v207, v0
	v_pk_mul_f32 v[78:79], v[78:79], v[0:1] op_sel_hi:[1,0]
	v_pk_mul_f32 v[76:77], v[76:77], v[0:1] op_sel_hi:[1,0]
	v_pk_mul_f32 v[74:75], v[74:75], v[0:1] op_sel_hi:[1,0]
	v_pk_mul_f32 v[72:73], v[72:73], v[0:1] op_sel_hi:[1,0]
	v_pk_mul_f32 v[70:71], v[70:71], v[0:1] op_sel_hi:[1,0]
	v_pk_mul_f32 v[68:69], v[68:69], v[0:1] op_sel_hi:[1,0]
	v_pk_mul_f32 v[66:67], v[66:67], v[0:1] op_sel_hi:[1,0]
	v_pk_mul_f32 v[64:65], v[64:65], v[0:1] op_sel_hi:[1,0]
	v_pk_mul_f32 v[62:63], v[62:63], v[0:1] op_sel_hi:[1,0]
	v_pk_mul_f32 v[60:61], v[60:61], v[0:1] op_sel_hi:[1,0]
	v_pk_mul_f32 v[58:59], v[58:59], v[0:1] op_sel_hi:[1,0]
	v_pk_mul_f32 v[56:57], v[56:57], v[0:1] op_sel_hi:[1,0]
	v_pk_mul_f32 v[54:55], v[54:55], v[0:1] op_sel_hi:[1,0]
	v_pk_mul_f32 v[52:53], v[52:53], v[0:1] op_sel_hi:[1,0]
	v_pk_mul_f32 v[50:51], v[50:51], v[0:1] op_sel_hi:[1,0]
	v_pk_mul_f32 v[48:49], v[48:49], v[0:1] op_sel_hi:[1,0]

; __device__ __forceinline__ float max3f(float a, float b, float c) { return fmaxf(fmaxf(a, b), c); }
; __device__ __forceinline__ float max2f(float a, float b) { return fmaxf(a, b); }
; __device__ __forceinline__ void softmax_head(f32x16& s, int kb, int lq, int radius, bool full, int hi, HState& S) {
;     ...
;     float t0 = max3f(s[0], s[1], s[2]), t1 = max3f(s[3], s[4], s[5]);
;     t0 = max3f(t0, s[6], s[7]); t1 = max3f(t1, s[8], s[9]); t0 = max3f(t0, s[10], s[11]); t1 = max3f(t1, s[12], s[13]);
;     float tmax = max3f(t0, s[14], s[15]); tmax = max2f(tmax, t1);
;     { auto rr = __builtin_amdgcn_permlane32_swap(__float_as_uint(tmax), __float_as_uint(tmax), false, false); tmax = max2f(__uint_as_float(rr[0]), __uint_as_float(rr[1])); }
;     if (__builtin_amdgcn_ballot_w64(tmax > S.m + 8.0f) != 0ull) {
;         const float mn = max2f(S.m, tmax), alpha = __builtin_amdgcn_exp2f(S.m - mn); S.m = mn; S.l *= alpha;
; #pragma unroll
;         for (int dh = 0; dh < 2; ++dh)
; #pragma unroll
;             for (int r = 0; r < 16; ++r) S.o[dh][r] *= alpha;
;     }
.LBB0_554:
	s_nop 3
	v_max_f32_e32 v15, v96, v97
	v_max3_f32 v148, v99, v100, v101
	v_max3_f32 v15, v15, v98, v102
	v_max3_f32 v148, v148, v104, v105
	v_max3_f32 v15, v15, v103, v106
	v_max3_f32 v148, v148, v108, v109
	v_max3_f32 v15, v15, v107, v110
	v_max3_f32 v15, v15, v111, v148
	v_mov_b32_e32 v148, v15
	s_nop 1
	v_permlane32_swap_b32_e32 v15, v148
	v_max_f32_e32 v15, v15, v148
	v_add_f32_e32 v148, 0x41000000, v185
	v_cmp_gt_f32_e32 vcc, v15, v148
	s_cbranch_vccz .LBB0_556
	v_max_f32_e32 v15, v15, v15
	v_max_f32_e32 v148, v185, v185
	v_max_f32_e32 v15, v148, v15
	v_sub_f32_e32 v148, v185, v15
	v_exp_f32_e32 v148, v148
	v_mov_b32_e32 v185, v15
	v_mul_f32_e32 v186, v186, v148
	v_pk_mul_f32 v[46:47], v[46:47], v[148:149] op_sel_hi:[1,0]
	v_pk_mul_f32 v[44:45], v[44:45], v[148:149] op_sel_hi:[1,0]
	v_pk_mul_f32 v[42:43], v[42:43], v[148:149] op_sel_hi:[1,0]
	v_pk_mul_f32 v[40:41], v[40:41], v[148:149] op_sel_hi:[1,0]
	v_pk_mul_f32 v[38:39], v[38:39], v[148:149] op_sel_hi:[1,0]
	v_pk_mul_f32 v[36:37], v[36:37], v[148:149] op_sel_hi:[1,0]
	v_pk_mul_f32 v[34:35], v[34:35], v[148:149] op_sel_hi:[1,0]
	v_pk_mul_f32 v[32:33], v[32:33], v[148:149] op_sel_hi:[1,0]
	v_pk_mul_f32 v[30:31], v[30:31], v[148:149] op_sel_hi:[1,0]
	v_pk_mul_f32 v[28:29], v[28:29], v[148:149] op_sel_hi:[1,0]
	v_pk_mul_f32 v[26:27], v[26:27], v[148:149] op_sel_hi:[1,0]
	v_pk_mul_f32 v[24:25], v[24:25], v[148:149] op_sel_hi:[1,0]
	v_pk_mul_f32 v[22:23], v[22:23], v[148:149] op_sel_hi:[1,0]
	v_pk_mul_f32 v[20:21], v[20:21], v[148:149] op_sel_hi:[1,0]
	v_pk_mul_f32 v[18:19], v[18:19], v[148:149] op_sel_hi:[1,0]
	v_pk_mul_f32 v[16:17], v[16:17], v[148:149] op_sel_hi:[1,0]

; __device__ __forceinline__ float max3f(float a, float b, float c) { return fmaxf(fmaxf(a, b), c); }
; __device__ __forceinline__ float max2f(float a, float b) { return fmaxf(a, b); }
; __device__ __forceinline__ void softmax_head(f32x16& s, int kb, int lq, int radius, bool full, int hi, HState& S) {
;     ...
;     float t0 = max3f(s[0], s[1], s[2]), t1 = max3f(s[3], s[4], s[5]);
;     t0 = max3f(t0, s[6], s[7]); t1 = max3f(t1, s[8], s[9]); t0 = max3f(t0, s[10], s[11]); t1 = max3f(t1, s[12], s[13]);
;     float tmax = max3f(t0, s[14], s[15]); tmax = max2f(tmax, t1);
;     { auto rr = __builtin_amdgcn_permlane32_swap(__float_as_uint(tmax), __float_as_uint(tmax), false, false); tmax = max2f(__uint_as_float(rr[0]), __uint_as_float(rr[1])); }
;     if (__builtin_amdgcn_ballot_w64(tmax > S.m + 8.0f) != 0ull) {
;         const float mn = max2f(S.m, tmax), alpha = __builtin_amdgcn_exp2f(S.m - mn); S.m = mn; S.l *= alpha;
; #pragma unroll
;         for (int dh = 0; dh < 2; ++dh)
; #pragma unroll
;             for (int r = 0; r < 16; ++r) S.o[dh][r] *= alpha;
;     }
; __device__ __forceinline__ void softmax_tail(f32x16& s, HState& S, u32x4 (&pw)[2]) {
;     ...
;     float p0 = s[0], p1 = s[1];
; #pragma unroll
;     for (int r = 2; r < 16; r += 2) { p0 += s[r]; p1 += s[r + 1]; }
;     S.l += p0 + p1;
.LBB0_558:
	v_add_f32_e32 v14, v239, v241
	v_add_f32_e32 v100, v240, v242
	v_add_f32_e32 v14, v243, v14
	v_add_f32_e32 v100, v244, v100
	v_add_f32_e32 v14, v245, v14
	v_add_f32_e32 v100, v246, v100
	v_add_f32_e32 v14, v247, v14
	v_add_f32_e32 v100, v248, v100
	v_add_f32_e32 v14, v249, v14
	v_add_f32_e32 v100, v250, v100
	v_add_f32_e32 v14, v251, v14
	v_add_f32_e32 v100, v252, v100
	v_add_f32_e32 v14, v201, v14
	v_add_f32_e32 v100, v203, v100
	v_add_f32_e32 v14, v14, v100
	v_max_f32_e32 v100, v80, v81
	v_max3_f32 v101, v83, v84, v85
	v_max3_f32 v100, v100, v82, v86
	v_max3_f32 v101, v101, v88, v89
	v_max3_f32 v100, v100, v87, v90
	v_max3_f32 v101, v101, v92, v93
	v_max3_f32 v100, v100, v91, v94
	v_max3_f32 v100, v100, v95, v101
	v_mov_b32_e32 v101, v100
	s_nop 1
	v_permlane32_swap_b32_e32 v100, v101
	v_max_f32_e32 v100, v100, v101
	v_add_f32_e32 v101, 0x41000000, v196
	v_add_f32_e32 v14, v207, v14
	v_cmp_gt_f32_e32 vcc, v100, v101
	s_cbranch_vccz .LBB0_560
	v_max_f32_e32 v100, v100, v100
	v_max_f32_e32 v101, v196, v196
	v_max_f32_e32 v101, v101, v100
	v_sub_f32_e32 v100, v196, v101
	v_exp_f32_e32 v100, v100
	v_mov_b32_e32 v196, v101
	v_mul_f32_e32 v14, v14, v100
	v_pk_mul_f32 v[78:79], v[78:79], v[100:101] op_sel_hi:[1,0]
	v_pk_mul_f32 v[76:77], v[76:77], v[100:101] op_sel_hi:[1,0]
	v_pk_mul_f32 v[74:75], v[74:75], v[100:101] op_sel_hi:[1,0]
	v_pk_mul_f32 v[72:73], v[72:73], v[100:101] op_sel_hi:[1,0]
	v_pk_mul_f32 v[70:71], v[70:71], v[100:101] op_sel_hi:[1,0]
	v_pk_mul_f32 v[68:69], v[68:69], v[100:101] op_sel_hi:[1,0]
	v_pk_mul_f32 v[66:67], v[66:67], v[100:101] op_sel_hi:[1,0]
	v_pk_mul_f32 v[64:65], v[64:65], v[100:101] op_sel_hi:[1,0]
	v_pk_mul_f32 v[62:63], v[62:63], v[100:101] op_sel_hi:[1,0]
	v_pk_mul_f32 v[60:61], v[60:61], v[100:101] op_sel_hi:[1,0]
	v_pk_mul_f32 v[58:59], v[58:59], v[100:101] op_sel_hi:[1,0]
	v_pk_mul_f32 v[56:57], v[56:57], v[100:101] op_sel_hi:[1,0]
	v_pk_mul_f32 v[54:55], v[54:55], v[100:101] op_sel_hi:[1,0]
	v_pk_mul_f32 v[52:53], v[52:53], v[100:101] op_sel_hi:[1,0]
	v_pk_mul_f32 v[50:51], v[50:51], v[100:101] op_sel_hi:[1,0]
	v_pk_mul_f32 v[48:49], v[48:49], v[100:101] op_sel_hi:[1,0]

; __device__ __forceinline__ float max3f(float a, float b, float c) { return fmaxf(fmaxf(a, b), c); }
; __device__ __forceinline__ float max2f(float a, float b) { return fmaxf(a, b); }
; __device__ __forceinline__ void softmax_head(f32x16& s, int kb, int lq, int radius, bool full, int hi, HState& S) {
;     ...
;     float t0 = max3f(s[0], s[1], s[2]), t1 = max3f(s[3], s[4], s[5]);
;     t0 = max3f(t0, s[6], s[7]); t1 = max3f(t1, s[8], s[9]); t0 = max3f(t0, s[10], s[11]); t1 = max3f(t1, s[12], s[13]);
;     float tmax = max3f(t0, s[14], s[15]); tmax = max2f(tmax, t1);
;     { auto rr = __builtin_amdgcn_permlane32_swap(__float_as_uint(tmax), __float_as_uint(tmax), false, false); tmax = max2f(__uint_as_float(rr[0]), __uint_as_float(rr[1])); }
;     if (__builtin_amdgcn_ballot_w64(tmax > S.m + 8.0f) != 0ull) {
;         const float mn = max2f(S.m, tmax), alpha = __builtin_amdgcn_exp2f(S.m - mn); S.m = mn; S.l *= alpha;
; #pragma unroll
;         for (int dh = 0; dh < 2; ++dh)
; #pragma unroll
;             for (int r = 0; r < 16; ++r) S.o[dh][r] *= alpha;
;     }
; __device__ __forceinline__ void softmax_tail(f32x16& s, HState& S, u32x4 (&pw)[2]) {
;     ...
;     float p0 = s[0], p1 = s[1];
; #pragma unroll
;     for (int r = 2; r < 16; r += 2) { p0 += s[r]; p1 += s[r + 1]; }
;     S.l += p0 + p1;
.LBB0_562:
	v_add_f32_e32 v0, v15, v225
	v_add_f32_e32 v15, v224, v226
	v_add_f32_e32 v0, v227, v0
	v_add_f32_e32 v15, v228, v15
	v_add_f32_e32 v0, v229, v0
	v_add_f32_e32 v15, v230, v15
	v_add_f32_e32 v0, v231, v0
	v_add_f32_e32 v15, v232, v15
	v_add_f32_e32 v0, v233, v0
	v_add_f32_e32 v15, v234, v15
	v_add_f32_e32 v0, v235, v0
	v_add_f32_e32 v15, v236, v15
	v_add_f32_e32 v0, v237, v0
	v_add_f32_e32 v15, v238, v15
	v_add_f32_e32 v0, v0, v15
	v_max_f32_e32 v15, v96, v97
	v_max3_f32 v148, v99, v100, v101
	v_max3_f32 v15, v15, v98, v102
	v_max3_f32 v148, v148, v104, v105
	v_max3_f32 v15, v15, v103, v106
	v_max3_f32 v148, v148, v108, v109
	v_max3_f32 v15, v15, v107, v110
	v_max3_f32 v15, v15, v111, v148
	v_mov_b32_e32 v148, v15
	s_nop 1
	v_permlane32_swap_b32_e32 v15, v148
	v_max_f32_e32 v15, v15, v148
	v_add_f32_e32 v148, 0x41000000, v185
	v_add_f32_e32 v0, v186, v0
	v_cmp_gt_f32_e32 vcc, v15, v148
	s_cbranch_vccz .LBB0_564
	v_max_f32_e32 v15, v15, v15
	v_max_f32_e32 v148, v185, v185
	v_max_f32_e32 v15, v148, v15
	v_sub_f32_e32 v148, v185, v15
	v_exp_f32_e32 v148, v148
	v_mov_b32_e32 v185, v15
	v_mul_f32_e32 v0, v0, v148
	v_pk_mul_f32 v[46:47], v[46:47], v[148:149] op_sel_hi:[1,0]
	v_pk_mul_f32 v[44:45], v[44:45], v[148:149] op_sel_hi:[1,0]
	v_pk_mul_f32 v[42:43], v[42:43], v[148:149] op_sel_hi:[1,0]
	v_pk_mul_f32 v[40:41], v[40:41], v[148:149] op_sel_hi:[1,0]
	v_pk_mul_f32 v[38:39], v[38:39], v[148:149] op_sel_hi:[1,0]
	v_pk_mul_f32 v[36:37], v[36:37], v[148:149] op_sel_hi:[1,0]
	v_pk_mul_f32 v[34:35], v[34:35], v[148:149] op_sel_hi:[1,0]
	v_pk_mul_f32 v[32:33], v[32:33], v[148:149] op_sel_hi:[1,0]
	v_pk_mul_f32 v[30:31], v[30:31], v[148:149] op_sel_hi:[1,0]
	v_pk_mul_f32 v[28:29], v[28:29], v[148:149] op_sel_hi:[1,0]
	v_pk_mul_f32 v[26:27], v[26:27], v[148:149] op_sel_hi:[1,0]
	v_pk_mul_f32 v[24:25], v[24:25], v[148:149] op_sel_hi:[1,0]
	v_pk_mul_f32 v[22:23], v[22:23], v[148:149] op_sel_hi:[1,0]
	v_pk_mul_f32 v[20:21], v[20:21], v[148:149] op_sel_hi:[1,0]
	v_pk_mul_f32 v[18:19], v[18:19], v[148:149] op_sel_hi:[1,0]
	v_pk_mul_f32 v[16:17], v[16:17], v[148:149] op_sel_hi:[1,0]

; __device__ __forceinline__ float max3f(float a, float b, float c) { return fmaxf(fmaxf(a, b), c); }
; __device__ __forceinline__ float max2f(float a, float b) { return fmaxf(a, b); }
; __device__ __forceinline__ void softmax_head(f32x16& s, int kb, int lq, int radius, bool full, int hi, HState& S) {
;     ...
;     float t0 = max3f(s[0], s[1], s[2]), t1 = max3f(s[3], s[4], s[5]);
;     t0 = max3f(t0, s[6], s[7]); t1 = max3f(t1, s[8], s[9]); t0 = max3f(t0, s[10], s[11]); t1 = max3f(t1, s[12], s[13]);
;     float tmax = max3f(t0, s[14], s[15]); tmax = max2f(tmax, t1);
;     { auto rr = __builtin_amdgcn_permlane32_swap(__float_as_uint(tmax), __float_as_uint(tmax), false, false); tmax = max2f(__uint_as_float(rr[0]), __uint_as_float(rr[1])); }
;     if (__builtin_amdgcn_ballot_w64(tmax > S.m + 8.0f) != 0ull) {
;         const float mn = max2f(S.m, tmax), alpha = __builtin_amdgcn_exp2f(S.m - mn); S.m = mn; S.l *= alpha;
; #pragma unroll
;         for (int dh = 0; dh < 2; ++dh)
; #pragma unroll
;             for (int r = 0; r < 16; ++r) S.o[dh][r] *= alpha;
;     }
.LBB0_569:
	s_nop 10
	v_max_f32_e32 v14, v80, v81
	v_max3_f32 v15, v83, v84, v85
	v_max3_f32 v14, v14, v82, v86
	v_max3_f32 v15, v15, v88, v89
	v_max3_f32 v14, v14, v87, v90
	v_max3_f32 v15, v15, v92, v93
	v_max3_f32 v14, v14, v91, v94
	v_max3_f32 v14, v14, v95, v15
	v_mov_b32_e32 v15, v14
	s_nop 1
	v_permlane32_swap_b32_e32 v14, v15
	v_max_f32_e32 v14, v14, v15
	v_add_f32_e32 v15, 0x41000000, v196
	v_cmp_gt_f32_e32 vcc, v14, v15
	s_cbranch_vccz .LBB0_571
	v_max_f32_e32 v14, v14, v14
	v_max_f32_e32 v15, v196, v196
	v_max_f32_e32 v15, v15, v14
	v_sub_f32_e32 v14, v196, v15
	v_exp_f32_e32 v14, v14
	v_mov_b32_e32 v196, v15
	v_mul_f32_e32 v207, v207, v14
	v_pk_mul_f32 v[78:79], v[78:79], v[14:15] op_sel_hi:[1,0]
	v_pk_mul_f32 v[76:77], v[76:77], v[14:15] op_sel_hi:[1,0]
	v_pk_mul_f32 v[74:75], v[74:75], v[14:15] op_sel_hi:[1,0]
	v_pk_mul_f32 v[72:73], v[72:73], v[14:15] op_sel_hi:[1,0]
	v_pk_mul_f32 v[70:71], v[70:71], v[14:15] op_sel_hi:[1,0]
	v_pk_mul_f32 v[68:69], v[68:69], v[14:15] op_sel_hi:[1,0]
	v_pk_mul_f32 v[66:67], v[66:67], v[14:15] op_sel_hi:[1,0]
	v_pk_mul_f32 v[64:65], v[64:65], v[14:15] op_sel_hi:[1,0]
	v_pk_mul_f32 v[62:63], v[62:63], v[14:15] op_sel_hi:[1,0]
	v_pk_mul_f32 v[60:61], v[60:61], v[14:15] op_sel_hi:[1,0]
	v_pk_mul_f32 v[58:59], v[58:59], v[14:15] op_sel_hi:[1,0]
	v_pk_mul_f32 v[56:57], v[56:57], v[14:15] op_sel_hi:[1,0]
	v_pk_mul_f32 v[54:55], v[54:55], v[14:15] op_sel_hi:[1,0]
	v_pk_mul_f32 v[52:53], v[52:53], v[14:15] op_sel_hi:[1,0]
	v_pk_mul_f32 v[50:51], v[50:51], v[14:15] op_sel_hi:[1,0]
	v_pk_mul_f32 v[48:49], v[48:49], v[14:15] op_sel_hi:[1,0]

; __device__ __forceinline__ float max3f(float a, float b, float c) { return fmaxf(fmaxf(a, b), c); }
; __device__ __forceinline__ float max2f(float a, float b) { return fmaxf(a, b); }
; __device__ __forceinline__ void softmax_head(f32x16& s, int kb, int lq, int radius, bool full, int hi, HState& S) {
;     ...
;     float t0 = max3f(s[0], s[1], s[2]), t1 = max3f(s[3], s[4], s[5]);
;     t0 = max3f(t0, s[6], s[7]); t1 = max3f(t1, s[8], s[9]); t0 = max3f(t0, s[10], s[11]); t1 = max3f(t1, s[12], s[13]);
;     float tmax = max3f(t0, s[14], s[15]); tmax = max2f(tmax, t1);
;     { auto rr = __builtin_amdgcn_permlane32_swap(__float_as_uint(tmax), __float_as_uint(tmax), false, false); tmax = max2f(__uint_as_float(rr[0]), __uint_as_float(rr[1])); }
;     if (__builtin_amdgcn_ballot_w64(tmax > S.m + 8.0f) != 0ull) {
;         const float mn = max2f(S.m, tmax), alpha = __builtin_amdgcn_exp2f(S.m - mn); S.m = mn; S.l *= alpha;
; #pragma unroll
;         for (int dh = 0; dh < 2; ++dh)
; #pragma unroll
;             for (int r = 0; r < 16; ++r) S.o[dh][r] *= alpha;
;     }
.LBB0_573:
	s_nop 3
	v_max_f32_e32 v0, v96, v97
	v_max3_f32 v14, v99, v100, v101
	v_max3_f32 v0, v0, v98, v102
	v_max3_f32 v14, v14, v104, v105
	v_max3_f32 v0, v0, v103, v106
	v_max3_f32 v14, v14, v108, v109
	v_max3_f32 v0, v0, v107, v110
	v_max3_f32 v0, v0, v111, v14
	v_mov_b32_e32 v14, v0
	s_nop 1
	v_permlane32_swap_b32_e32 v0, v14
	v_max_f32_e32 v0, v0, v14
	v_add_f32_e32 v14, 0x41000000, v185
	v_cmp_gt_f32_e32 vcc, v0, v14
	s_cbranch_vccz .LBB0_575
	v_max_f32_e32 v0, v0, v0
	v_max_f32_e32 v14, v185, v185
	v_max_f32_e32 v14, v14, v0
	v_sub_f32_e32 v0, v185, v14
	v_exp_f32_e32 v0, v0
	v_mov_b32_e32 v185, v14
	v_mul_f32_e32 v186, v186, v0
	v_pk_mul_f32 v[46:47], v[46:47], v[0:1] op_sel_hi:[1,0]
	v_pk_mul_f32 v[44:45], v[44:45], v[0:1] op_sel_hi:[1,0]
	v_pk_mul_f32 v[42:43], v[42:43], v[0:1] op_sel_hi:[1,0]
	v_pk_mul_f32 v[40:41], v[40:41], v[0:1] op_sel_hi:[1,0]
	v_pk_mul_f32 v[38:39], v[38:39], v[0:1] op_sel_hi:[1,0]
	v_pk_mul_f32 v[36:37], v[36:37], v[0:1] op_sel_hi:[1,0]
	v_pk_mul_f32 v[34:35], v[34:35], v[0:1] op_sel_hi:[1,0]
	v_pk_mul_f32 v[32:33], v[32:33], v[0:1] op_sel_hi:[1,0]
	v_pk_mul_f32 v[30:31], v[30:31], v[0:1] op_sel_hi:[1,0]
	v_pk_mul_f32 v[28:29], v[28:29], v[0:1] op_sel_hi:[1,0]
	v_pk_mul_f32 v[26:27], v[26:27], v[0:1] op_sel_hi:[1,0]
	v_pk_mul_f32 v[24:25], v[24:25], v[0:1] op_sel_hi:[1,0]
	v_pk_mul_f32 v[22:23], v[22:23], v[0:1] op_sel_hi:[1,0]
	v_pk_mul_f32 v[20:21], v[20:21], v[0:1] op_sel_hi:[1,0]
	v_pk_mul_f32 v[18:19], v[18:19], v[0:1] op_sel_hi:[1,0]
	v_pk_mul_f32 v[16:17], v[16:17], v[0:1] op_sel_hi:[1,0]

; __device__ __forceinline__ float max3f(float a, float b, float c) { return fmaxf(fmaxf(a, b), c); }
; __device__ __forceinline__ float max2f(float a, float b) { return fmaxf(a, b); }
; __device__ __forceinline__ void softmax_head(f32x16& s, int kb, int lq, int radius, bool full, int hi, HState& S) {
;     ...
;     float t0 = max3f(s[0], s[1], s[2]), t1 = max3f(s[3], s[4], s[5]);
;     t0 = max3f(t0, s[6], s[7]); t1 = max3f(t1, s[8], s[9]); t0 = max3f(t0, s[10], s[11]); t1 = max3f(t1, s[12], s[13]);
;     float tmax = max3f(t0, s[14], s[15]); tmax = max2f(tmax, t1);
;     { auto rr = __builtin_amdgcn_permlane32_swap(__float_as_uint(tmax), __float_as_uint(tmax), false, false); tmax = max2f(__uint_as_float(rr[0]), __uint_as_float(rr[1])); }
;     if (__builtin_amdgcn_ballot_w64(tmax > S.m + 8.0f) != 0ull) {
;         const float mn = max2f(S.m, tmax), alpha = __builtin_amdgcn_exp2f(S.m - mn); S.m = mn; S.l *= alpha;
; #pragma unroll
;         for (int dh = 0; dh < 2; ++dh)
; #pragma unroll
;             for (int r = 0; r < 16; ++r) S.o[dh][r] *= alpha;
;     }
.LBB0_580:
	s_nop 10
	v_max_f32_e32 v135, v80, v81
	v_max3_f32 v136, v83, v84, v85
	v_max3_f32 v135, v135, v82, v86
	v_max3_f32 v136, v136, v88, v89
	v_max3_f32 v135, v135, v87, v90
	v_max3_f32 v136, v136, v92, v93
	v_max3_f32 v135, v135, v91, v94
	v_max3_f32 v135, v135, v95, v136
	v_mov_b32_e32 v136, v135
	s_nop 1
	v_permlane32_swap_b32_e32 v135, v136
	v_max_f32_e32 v135, v135, v136
	v_add_f32_e32 v136, 0x41000000, v196
	v_cmp_gt_f32_e32 vcc, v135, v136
	s_cbranch_vccz .LBB0_582
	v_max_f32_e32 v135, v135, v135
	v_max_f32_e32 v136, v196, v196
	v_max_f32_e32 v135, v136, v135
	v_sub_f32_e32 v136, v196, v135
	v_exp_f32_e32 v136, v136
	v_mov_b32_e32 v196, v135
	v_mul_f32_e32 v207, v207, v136
	v_pk_mul_f32 v[78:79], v[78:79], v[136:137] op_sel_hi:[1,0]
	v_pk_mul_f32 v[76:77], v[76:77], v[136:137] op_sel_hi:[1,0]
	v_pk_mul_f32 v[74:75], v[74:75], v[136:137] op_sel_hi:[1,0]
	v_pk_mul_f32 v[72:73], v[72:73], v[136:137] op_sel_hi:[1,0]
	v_pk_mul_f32 v[70:71], v[70:71], v[136:137] op_sel_hi:[1,0]
	v_pk_mul_f32 v[68:69], v[68:69], v[136:137] op_sel_hi:[1,0]
	v_pk_mul_f32 v[66:67], v[66:67], v[136:137] op_sel_hi:[1,0]
	v_pk_mul_f32 v[64:65], v[64:65], v[136:137] op_sel_hi:[1,0]
	v_pk_mul_f32 v[62:63], v[62:63], v[136:137] op_sel_hi:[1,0]
	v_pk_mul_f32 v[60:61], v[60:61], v[136:137] op_sel_hi:[1,0]
	v_pk_mul_f32 v[58:59], v[58:59], v[136:137] op_sel_hi:[1,0]
	v_pk_mul_f32 v[56:57], v[56:57], v[136:137] op_sel_hi:[1,0]
	v_pk_mul_f32 v[54:55], v[54:55], v[136:137] op_sel_hi:[1,0]
	v_pk_mul_f32 v[52:53], v[52:53], v[136:137] op_sel_hi:[1,0]
	v_pk_mul_f32 v[50:51], v[50:51], v[136:137] op_sel_hi:[1,0]
	v_pk_mul_f32 v[48:49], v[48:49], v[136:137] op_sel_hi:[1,0]

; __device__ __forceinline__ float max3f(float a, float b, float c) { return fmaxf(fmaxf(a, b), c); }
; __device__ __forceinline__ float max2f(float a, float b) { return fmaxf(a, b); }
; __device__ __forceinline__ void softmax_head(f32x16& s, int kb, int lq, int radius, bool full, int hi, HState& S) {
;     ...
;     float t0 = max3f(s[0], s[1], s[2]), t1 = max3f(s[3], s[4], s[5]);
;     t0 = max3f(t0, s[6], s[7]); t1 = max3f(t1, s[8], s[9]); t0 = max3f(t0, s[10], s[11]); t1 = max3f(t1, s[12], s[13]);
;     float tmax = max3f(t0, s[14], s[15]); tmax = max2f(tmax, t1);
;     { auto rr = __builtin_amdgcn_permlane32_swap(__float_as_uint(tmax), __float_as_uint(tmax), false, false); tmax = max2f(__uint_as_float(rr[0]), __uint_as_float(rr[1])); }
;     if (__builtin_amdgcn_ballot_w64(tmax > S.m + 8.0f) != 0ull) {
;         const float mn = max2f(S.m, tmax), alpha = __builtin_amdgcn_exp2f(S.m - mn); S.m = mn; S.l *= alpha;
; #pragma unroll
;         for (int dh = 0; dh < 2; ++dh)
; #pragma unroll
;             for (int r = 0; r < 16; ++r) S.o[dh][r] *= alpha;
;     }
; __device__ __forceinline__ void softmax_tail(f32x16& s, HState& S, u32x4 (&pw)[2]) {
;     ...
;     float p0 = s[0], p1 = s[1];
; #pragma unroll
;     for (int r = 2; r < 16; r += 2) { p0 += s[r]; p1 += s[r + 1]; }
;     S.l += p0 + p1;
.LBB0_584:
	v_add_f32_e32 v133, v135, v137
	v_add_f32_e32 v135, v136, v138
	v_add_f32_e32 v133, v139, v133
	v_add_f32_e32 v135, v140, v135
	v_add_f32_e32 v133, v141, v133
	v_add_f32_e32 v135, v142, v135
	v_add_f32_e32 v133, v143, v133
	v_add_f32_e32 v135, v146, v135
	v_add_f32_e32 v133, v147, v133
	v_add_f32_e32 v135, v148, v135
	v_add_f32_e32 v133, v149, v133
	v_add_f32_e32 v135, v150, v135
	v_add_f32_e32 v133, v151, v133
	v_add_f32_e32 v135, v152, v135
	v_add_f32_e32 v133, v133, v135
	v_max_f32_e32 v135, v80, v81
	v_max3_f32 v136, v83, v84, v85
	v_max3_f32 v135, v135, v82, v86
	v_max3_f32 v136, v136, v88, v89
	v_max3_f32 v135, v135, v87, v90
	v_max3_f32 v136, v136, v92, v93
	v_max3_f32 v135, v135, v91, v94
	v_max3_f32 v135, v135, v95, v136
	v_mov_b32_e32 v136, v135
	s_nop 1
	v_permlane32_swap_b32_e32 v135, v136
	v_max_f32_e32 v135, v135, v136
	v_add_f32_e32 v136, 0x41000000, v196
	v_add_f32_e32 v133, v207, v133
	v_cmp_gt_f32_e32 vcc, v135, v136
	s_cbranch_vccz .LBB0_586
	v_max_f32_e32 v135, v135, v135
	v_max_f32_e32 v136, v196, v196
	v_max_f32_e32 v135, v136, v135
	v_sub_f32_e32 v136, v196, v135
	v_exp_f32_e32 v136, v136
	v_mov_b32_e32 v196, v135
	v_mul_f32_e32 v133, v133, v136
	v_pk_mul_f32 v[78:79], v[78:79], v[136:137] op_sel_hi:[1,0]
	v_pk_mul_f32 v[76:77], v[76:77], v[136:137] op_sel_hi:[1,0]
	v_pk_mul_f32 v[74:75], v[74:75], v[136:137] op_sel_hi:[1,0]
	v_pk_mul_f32 v[72:73], v[72:73], v[136:137] op_sel_hi:[1,0]
	v_pk_mul_f32 v[70:71], v[70:71], v[136:137] op_sel_hi:[1,0]
	v_pk_mul_f32 v[68:69], v[68:69], v[136:137] op_sel_hi:[1,0]
	v_pk_mul_f32 v[66:67], v[66:67], v[136:137] op_sel_hi:[1,0]
	v_pk_mul_f32 v[64:65], v[64:65], v[136:137] op_sel_hi:[1,0]
	v_pk_mul_f32 v[62:63], v[62:63], v[136:137] op_sel_hi:[1,0]
	v_pk_mul_f32 v[60:61], v[60:61], v[136:137] op_sel_hi:[1,0]
	v_pk_mul_f32 v[58:59], v[58:59], v[136:137] op_sel_hi:[1,0]
	v_pk_mul_f32 v[56:57], v[56:57], v[136:137] op_sel_hi:[1,0]
	v_pk_mul_f32 v[54:55], v[54:55], v[136:137] op_sel_hi:[1,0]
	v_pk_mul_f32 v[52:53], v[52:53], v[136:137] op_sel_hi:[1,0]
	v_pk_mul_f32 v[50:51], v[50:51], v[136:137] op_sel_hi:[1,0]
	v_pk_mul_f32 v[48:49], v[48:49], v[136:137] op_sel_hi:[1,0]

; __device__ __forceinline__ float max3f(float a, float b, float c) { return fmaxf(fmaxf(a, b), c); }
; __device__ __forceinline__ float max2f(float a, float b) { return fmaxf(a, b); }
; __device__ __forceinline__ void softmax_head(f32x16& s, int kb, int lq, int radius, bool full, int hi, HState& S) {
;     ...
;     float t0 = max3f(s[0], s[1], s[2]), t1 = max3f(s[3], s[4], s[5]);
;     t0 = max3f(t0, s[6], s[7]); t1 = max3f(t1, s[8], s[9]); t0 = max3f(t0, s[10], s[11]); t1 = max3f(t1, s[12], s[13]);
;     float tmax = max3f(t0, s[14], s[15]); tmax = max2f(tmax, t1);
;     { auto rr = __builtin_amdgcn_permlane32_swap(__float_as_uint(tmax), __float_as_uint(tmax), false, false); tmax = max2f(__uint_as_float(rr[0]), __uint_as_float(rr[1])); }
;     if (__builtin_amdgcn_ballot_w64(tmax > S.m + 8.0f) != 0ull) {
;         const float mn = max2f(S.m, tmax), alpha = __builtin_amdgcn_exp2f(S.m - mn); S.m = mn; S.l *= alpha;
; #pragma unroll
;         for (int dh = 0; dh < 2; ++dh)
; #pragma unroll
;             for (int r = 0; r < 16; ++r) S.o[dh][r] *= alpha;
;     }
.LBB0_591:
	s_nop 10
	v_max_f32_e32 v100, v80, v81
	v_max3_f32 v101, v83, v84, v85
	v_max3_f32 v100, v100, v82, v86
	v_max3_f32 v101, v101, v88, v89
	v_max3_f32 v100, v100, v87, v90
	v_max3_f32 v101, v101, v92, v93
	v_max3_f32 v100, v100, v91, v94
	v_max3_f32 v100, v100, v95, v101
	v_mov_b32_e32 v101, v100
	s_nop 1
	v_permlane32_swap_b32_e32 v100, v101
	v_max_f32_e32 v100, v100, v101
	v_add_f32_e32 v101, 0x41000000, v196
	v_cmp_gt_f32_e32 vcc, v100, v101
	s_cbranch_vccz .LBB0_593
	v_max_f32_e32 v100, v100, v100
	v_max_f32_e32 v101, v196, v196
	v_max_f32_e32 v101, v101, v100
	v_sub_f32_e32 v100, v196, v101
	v_exp_f32_e32 v100, v100
	v_mov_b32_e32 v196, v101
	v_mul_f32_e32 v207, v207, v100
	v_pk_mul_f32 v[78:79], v[78:79], v[100:101] op_sel_hi:[1,0]
	v_pk_mul_f32 v[76:77], v[76:77], v[100:101] op_sel_hi:[1,0]
	v_pk_mul_f32 v[74:75], v[74:75], v[100:101] op_sel_hi:[1,0]
	v_pk_mul_f32 v[72:73], v[72:73], v[100:101] op_sel_hi:[1,0]
	v_pk_mul_f32 v[70:71], v[70:71], v[100:101] op_sel_hi:[1,0]
	v_pk_mul_f32 v[68:69], v[68:69], v[100:101] op_sel_hi:[1,0]
	v_pk_mul_f32 v[66:67], v[66:67], v[100:101] op_sel_hi:[1,0]
	v_pk_mul_f32 v[64:65], v[64:65], v[100:101] op_sel_hi:[1,0]
	v_pk_mul_f32 v[62:63], v[62:63], v[100:101] op_sel_hi:[1,0]
	v_pk_mul_f32 v[60:61], v[60:61], v[100:101] op_sel_hi:[1,0]
	v_pk_mul_f32 v[58:59], v[58:59], v[100:101] op_sel_hi:[1,0]
	v_pk_mul_f32 v[56:57], v[56:57], v[100:101] op_sel_hi:[1,0]
	v_pk_mul_f32 v[54:55], v[54:55], v[100:101] op_sel_hi:[1,0]
	v_pk_mul_f32 v[52:53], v[52:53], v[100:101] op_sel_hi:[1,0]
	v_pk_mul_f32 v[50:51], v[50:51], v[100:101] op_sel_hi:[1,0]
	v_pk_mul_f32 v[48:49], v[48:49], v[100:101] op_sel_hi:[1,0]

; __device__ __forceinline__ float max3f(float a, float b, float c) { return fmaxf(fmaxf(a, b), c); }
; __device__ __forceinline__ float max2f(float a, float b) { return fmaxf(a, b); }
; __device__ __forceinline__ void softmax_head(f32x16& s, int kb, int lq, int radius, bool full, int hi, HState& S) {
;     ...
;     float t0 = max3f(s[0], s[1], s[2]), t1 = max3f(s[3], s[4], s[5]);
;     t0 = max3f(t0, s[6], s[7]); t1 = max3f(t1, s[8], s[9]); t0 = max3f(t0, s[10], s[11]); t1 = max3f(t1, s[12], s[13]);
;     float tmax = max3f(t0, s[14], s[15]); tmax = max2f(tmax, t1);
;     { auto rr = __builtin_amdgcn_permlane32_swap(__float_as_uint(tmax), __float_as_uint(tmax), false, false); tmax = max2f(__uint_as_float(rr[0]), __uint_as_float(rr[1])); }
;     if (__builtin_amdgcn_ballot_w64(tmax > S.m + 8.0f) != 0ull) {
;         const float mn = max2f(S.m, tmax), alpha = __builtin_amdgcn_exp2f(S.m - mn); S.m = mn; S.l *= alpha;
; #pragma unroll
;         for (int dh = 0; dh < 2; ++dh)
; #pragma unroll
;             for (int r = 0; r < 16; ++r) S.o[dh][r] *= alpha;
;     }
.LBB0_598:
	s_nop 10
	v_max_f32_e32 v132, v80, v81
	v_max3_f32 v133, v83, v84, v85
	v_max3_f32 v132, v132, v82, v86
	v_max3_f32 v133, v133, v88, v89
	v_max3_f32 v132, v132, v87, v90
	v_max3_f32 v133, v133, v92, v93
	v_max3_f32 v132, v132, v91, v94
	v_max3_f32 v132, v132, v95, v133
	v_mov_b32_e32 v133, v132
	s_nop 1
	v_permlane32_swap_b32_e32 v132, v133
	v_max_f32_e32 v132, v132, v133
	v_add_f32_e32 v133, 0x41000000, v185
	v_cmp_gt_f32_e32 vcc, v132, v133
	s_cbranch_vccz .LBB0_600
	v_max_f32_e32 v132, v132, v132
	v_max_f32_e32 v133, v185, v185
	v_max_f32_e32 v133, v133, v132
	v_sub_f32_e32 v132, v185, v133
	v_exp_f32_e32 v132, v132
	v_mov_b32_e32 v185, v133
	v_mul_f32_e32 v186, v186, v132
	v_pk_mul_f32 v[46:47], v[46:47], v[132:133] op_sel_hi:[1,0]
	v_pk_mul_f32 v[44:45], v[44:45], v[132:133] op_sel_hi:[1,0]
	v_pk_mul_f32 v[42:43], v[42:43], v[132:133] op_sel_hi:[1,0]
	v_pk_mul_f32 v[40:41], v[40:41], v[132:133] op_sel_hi:[1,0]
	v_pk_mul_f32 v[38:39], v[38:39], v[132:133] op_sel_hi:[1,0]
	v_pk_mul_f32 v[36:37], v[36:37], v[132:133] op_sel_hi:[1,0]
	v_pk_mul_f32 v[34:35], v[34:35], v[132:133] op_sel_hi:[1,0]
	v_pk_mul_f32 v[32:33], v[32:33], v[132:133] op_sel_hi:[1,0]
	v_pk_mul_f32 v[30:31], v[30:31], v[132:133] op_sel_hi:[1,0]
	v_pk_mul_f32 v[28:29], v[28:29], v[132:133] op_sel_hi:[1,0]
	v_pk_mul_f32 v[26:27], v[26:27], v[132:133] op_sel_hi:[1,0]
	v_pk_mul_f32 v[24:25], v[24:25], v[132:133] op_sel_hi:[1,0]
	v_pk_mul_f32 v[22:23], v[22:23], v[132:133] op_sel_hi:[1,0]
	v_pk_mul_f32 v[20:21], v[20:21], v[132:133] op_sel_hi:[1,0]
	v_pk_mul_f32 v[18:19], v[18:19], v[132:133] op_sel_hi:[1,0]
	v_pk_mul_f32 v[16:17], v[16:17], v[132:133] op_sel_hi:[1,0]

; __device__ __forceinline__ float max3f(float a, float b, float c) { return fmaxf(fmaxf(a, b), c); }
; __device__ __forceinline__ float max2f(float a, float b) { return fmaxf(a, b); }
; __device__ __forceinline__ void softmax_head(f32x16& s, int kb, int lq, int radius, bool full, int hi, HState& S) {
;     ...
;     float t0 = max3f(s[0], s[1], s[2]), t1 = max3f(s[3], s[4], s[5]);
;     t0 = max3f(t0, s[6], s[7]); t1 = max3f(t1, s[8], s[9]); t0 = max3f(t0, s[10], s[11]); t1 = max3f(t1, s[12], s[13]);
;     float tmax = max3f(t0, s[14], s[15]); tmax = max2f(tmax, t1);
;     { auto rr = __builtin_amdgcn_permlane32_swap(__float_as_uint(tmax), __float_as_uint(tmax), false, false); tmax = max2f(__uint_as_float(rr[0]), __uint_as_float(rr[1])); }
;     if (__builtin_amdgcn_ballot_w64(tmax > S.m + 8.0f) != 0ull) {
;         const float mn = max2f(S.m, tmax), alpha = __builtin_amdgcn_exp2f(S.m - mn); S.m = mn; S.l *= alpha;
; #pragma unroll
;         for (int dh = 0; dh < 2; ++dh)
; #pragma unroll
;             for (int r = 0; r < 16; ++r) S.o[dh][r] *= alpha;
;     }
; __device__ __forceinline__ void softmax_tail(f32x16& s, HState& S, u32x4 (&pw)[2]) {
;     ...
;     float p0 = s[0], p1 = s[1];
; #pragma unroll
;     for (int r = 2; r < 16; r += 2) { p0 += s[r]; p1 += s[r + 1]; }
;     S.l += p0 + p1;
.LBB0_602:
	v_add_f32_e32 v15, v132, v135
	v_add_f32_e32 v132, v133, v136
	v_add_f32_e32 v15, v137, v15
	v_add_f32_e32 v132, v138, v132
	v_add_f32_e32 v15, v139, v15
	v_add_f32_e32 v132, v140, v132
	v_add_f32_e32 v15, v141, v15
	v_add_f32_e32 v132, v142, v132
	v_add_f32_e32 v15, v143, v15
	v_add_f32_e32 v132, v146, v132
	v_add_f32_e32 v15, v147, v15
	v_add_f32_e32 v132, v148, v132
	v_add_f32_e32 v15, v149, v15
	v_add_f32_e32 v132, v150, v132
	v_add_f32_e32 v15, v15, v132
	v_max_f32_e32 v132, v80, v81
	v_max3_f32 v133, v83, v84, v85
	v_max3_f32 v132, v132, v82, v86
	v_max3_f32 v133, v133, v88, v89
	v_max3_f32 v132, v132, v87, v90
	v_max3_f32 v133, v133, v92, v93
	v_max3_f32 v132, v132, v91, v94
	v_max3_f32 v132, v132, v95, v133
	v_mov_b32_e32 v133, v132
	s_nop 1
	v_permlane32_swap_b32_e32 v132, v133
	v_max_f32_e32 v132, v132, v133
	v_add_f32_e32 v133, 0x41000000, v185
	v_add_f32_e32 v15, v186, v15
	v_cmp_gt_f32_e32 vcc, v132, v133
	s_cbranch_vccz .LBB0_604
	v_max_f32_e32 v132, v132, v132
	v_max_f32_e32 v133, v185, v185
	v_max_f32_e32 v133, v133, v132
	v_sub_f32_e32 v132, v185, v133
	v_exp_f32_e32 v132, v132
	v_mov_b32_e32 v185, v133
	v_mul_f32_e32 v15, v15, v132
	v_pk_mul_f32 v[46:47], v[46:47], v[132:133] op_sel_hi:[1,0]
	v_pk_mul_f32 v[44:45], v[44:45], v[132:133] op_sel_hi:[1,0]
	v_pk_mul_f32 v[42:43], v[42:43], v[132:133] op_sel_hi:[1,0]
	v_pk_mul_f32 v[40:41], v[40:41], v[132:133] op_sel_hi:[1,0]
	v_pk_mul_f32 v[38:39], v[38:39], v[132:133] op_sel_hi:[1,0]
	v_pk_mul_f32 v[36:37], v[36:37], v[132:133] op_sel_hi:[1,0]
	v_pk_mul_f32 v[34:35], v[34:35], v[132:133] op_sel_hi:[1,0]
	v_pk_mul_f32 v[32:33], v[32:33], v[132:133] op_sel_hi:[1,0]
	v_pk_mul_f32 v[30:31], v[30:31], v[132:133] op_sel_hi:[1,0]
	v_pk_mul_f32 v[28:29], v[28:29], v[132:133] op_sel_hi:[1,0]
	v_pk_mul_f32 v[26:27], v[26:27], v[132:133] op_sel_hi:[1,0]
	v_pk_mul_f32 v[24:25], v[24:25], v[132:133] op_sel_hi:[1,0]
	v_pk_mul_f32 v[22:23], v[22:23], v[132:133] op_sel_hi:[1,0]
	v_pk_mul_f32 v[20:21], v[20:21], v[132:133] op_sel_hi:[1,0]
	v_pk_mul_f32 v[18:19], v[18:19], v[132:133] op_sel_hi:[1,0]
	v_pk_mul_f32 v[16:17], v[16:17], v[132:133] op_sel_hi:[1,0]

; __device__ __forceinline__ float max3f(float a, float b, float c) { return fmaxf(fmaxf(a, b), c); }
; __device__ __forceinline__ float max2f(float a, float b) { return fmaxf(a, b); }
; __device__ __forceinline__ void softmax_head(f32x16& s, int kb, int lq, int radius, bool full, int hi, HState& S) {
;     ...
;     float t0 = max3f(s[0], s[1], s[2]), t1 = max3f(s[3], s[4], s[5]);
;     t0 = max3f(t0, s[6], s[7]); t1 = max3f(t1, s[8], s[9]); t0 = max3f(t0, s[10], s[11]); t1 = max3f(t1, s[12], s[13]);
;     float tmax = max3f(t0, s[14], s[15]); tmax = max2f(tmax, t1);
;     { auto rr = __builtin_amdgcn_permlane32_swap(__float_as_uint(tmax), __float_as_uint(tmax), false, false); tmax = max2f(__uint_as_float(rr[0]), __uint_as_float(rr[1])); }
;     if (__builtin_amdgcn_ballot_w64(tmax > S.m + 8.0f) != 0ull) {
;         const float mn = max2f(S.m, tmax), alpha = __builtin_amdgcn_exp2f(S.m - mn); S.m = mn; S.l *= alpha;
; #pragma unroll
;         for (int dh = 0; dh < 2; ++dh)
; #pragma unroll
;             for (int r = 0; r < 16; ++r) S.o[dh][r] *= alpha;
;     }
.LBB0_609:
	s_nop 10
	v_max_f32_e32 v0, v80, v81
	v_max3_f32 v14, v83, v84, v85
	v_max3_f32 v0, v0, v82, v86
	v_max3_f32 v14, v14, v88, v89
	v_max3_f32 v0, v0, v87, v90
	v_max3_f32 v14, v14, v92, v93
	v_max3_f32 v0, v0, v91, v94
	v_max3_f32 v0, v0, v95, v14
	v_mov_b32_e32 v14, v0
	s_nop 1
	v_permlane32_swap_b32_e32 v0, v14
	v_max_f32_e32 v0, v0, v14
	v_add_f32_e32 v14, 0x41000000, v185
	v_cmp_gt_f32_e32 vcc, v0, v14
	s_cbranch_vccz .LBB0_545
	v_max_f32_e32 v0, v0, v0
	v_max_f32_e32 v14, v185, v185
	v_max_f32_e32 v14, v14, v0
	v_sub_f32_e32 v0, v185, v14
	v_exp_f32_e32 v0, v0
	v_mov_b32_e32 v185, v14
	v_mul_f32_e32 v186, v186, v0
	v_pk_mul_f32 v[46:47], v[46:47], v[0:1] op_sel_hi:[1,0]
	v_pk_mul_f32 v[44:45], v[44:45], v[0:1] op_sel_hi:[1,0]
	v_pk_mul_f32 v[42:43], v[42:43], v[0:1] op_sel_hi:[1,0]
	v_pk_mul_f32 v[40:41], v[40:41], v[0:1] op_sel_hi:[1,0]
	v_pk_mul_f32 v[38:39], v[38:39], v[0:1] op_sel_hi:[1,0]
	v_pk_mul_f32 v[36:37], v[36:37], v[0:1] op_sel_hi:[1,0]
	v_pk_mul_f32 v[34:35], v[34:35], v[0:1] op_sel_hi:[1,0]
	v_pk_mul_f32 v[32:33], v[32:33], v[0:1] op_sel_hi:[1,0]
	v_pk_mul_f32 v[30:31], v[30:31], v[0:1] op_sel_hi:[1,0]
	v_pk_mul_f32 v[28:29], v[28:29], v[0:1] op_sel_hi:[1,0]
	v_pk_mul_f32 v[26:27], v[26:27], v[0:1] op_sel_hi:[1,0]
	v_pk_mul_f32 v[24:25], v[24:25], v[0:1] op_sel_hi:[1,0]
	v_pk_mul_f32 v[22:23], v[22:23], v[0:1] op_sel_hi:[1,0]
	v_pk_mul_f32 v[20:21], v[20:21], v[0:1] op_sel_hi:[1,0]
	v_pk_mul_f32 v[18:19], v[18:19], v[0:1] op_sel_hi:[1,0]
	v_pk_mul_f32 v[16:17], v[16:17], v[0:1] op_sel_hi:[1,0]
	s_branch .LBB0_545
